# SSD inter-chunk MFMA group and off-diagonal block loop regenerated with batched/prefetched LDS reads; GEMM8/GEMM6 epilogue vectors loaded once up front instead of behind stores
# speedup vs baseline: 1.0647x; 1.0098x over previous
; #define PG8_STAGE(bufoff, gbase, voff) do { _Pragma("unroll") for (int _i = 0; _i < 2; ++_i) \
;         __builtin_amdgcn_global_load_lds((const unsigned*)((const char*)(gbase) + (voff)[_i]), (PG8_LAS unsigned*)(lds + (bufoff) + ldsw + _i * 8192), 16, 0, 0); } while (0)
; #define PG8_LDA(dst, b, h) do { _Pragma("unroll") for (int m = 0; m < 4; ++m) _Pragma("unroll") for (int k = 0; k < 2; ++k) dst[m][k] = *(const PG8_LAS bf16x8*)(lds + PG8_SA(b, h) + aoff + m * 2048 + k * 1024); } while (0)
; #define PG8_LDB(dst, b, h) do { _Pragma("unroll") for (int n = 0; n < 2; ++n) _Pragma("unroll") for (int k = 0; k < 2; ++k) dst[n][k] = *(const PG8_LAS bf16x8*)(lds + PG8_SB(b, h) + boff + n * 2048 + k * 1024); } while (0)
; #define PG8_MMA(ai, bj, At, Bt) do { __builtin_amdgcn_s_setprio(1); _Pragma("unroll") for (int m = 0; m < 4; ++m) _Pragma("unroll") for (int n = 0; n < 2; ++n) _Pragma("unroll") for (int k = 0; k < 2; ++k) \
;         acc[ai][bj][m][n] = __builtin_amdgcn_mfma_f32_16x16x32_bf16(Bt[n][k], At[m][k], acc[ai][bj][m][n], 0, 0, 0); __builtin_amdgcn_s_setprio(0); } while (0)
; #define PG8_WAIT_L(n) asm volatile("s_waitcnt lgkmcnt(" #n ")" ::: "memory")
; #define PG8_BAR __builtin_amdgcn_s_barrier()
; #define PG8_SCHED __builtin_amdgcn_sched_barrier(0)
; template <class Epi, class Sched>
; __device__ __forceinline__ void gemm_phase(PG8_LAS unsigned char* lds, const Gemm g, const Sched& S, const Epi& E, int tid_in) {
;     ...
;             PG8_LDB(B0, 0, 0); PG8_SCHED; PG8_LDA(At, 0, 0); PG8_STAGE(PG8_SA(1, 1), a1 + hstep, voffA);
;             PG8_WAIT_L(8); PG8_BAR; PG8_WAIT_L(0); PG8_MMA(0, 0, At, B0); PG8_BAR; PG8_SCHED;
;             PG8_LDB(B1, 0, 1); PG8_STAGE(PG8_SB(0, 0), b2, voffB);
;             PG8_BAR; PG8_WAIT_L(0); PG8_MMA(0, 1, At, B1); PG8_BAR;
;             PG8_LDA(At, 0, 1); PG8_STAGE(PG8_SA(0, 0), a2, voffA);
;             PG8_BAR; PG8_WAIT_L(0); PG8_MMA(1, 0, At, B0); PG8_BAR; PG8_SCHED;
.LBB0_295:
	s_add_u32 s24, s22, 0xfffc0080
	s_addc_u32 s25, s23, -1
	s_add_i32 s51, 0, 0x10000
	v_add_u32_e32 v154, s51, v151
	ds_read_b128 v[120:123], v154
	ds_read_b128 v[124:127], v154 offset:1024
	ds_read_b128 v[146:149], v154 offset:2048
	ds_read_b128 v[154:157], v154 offset:3072
	s_cmp_eq_u32 s50, 12
	s_cselect_b32 s27, s9, s25
	s_cselect_b32 s26, s45, s24
	s_cselect_b32 s25, s5, s49
	s_cselect_b32 s24, s46, s48
	v_lshl_add_u64 v[190:191], s[22:23], 0, v[142:143]
	s_add_i32 m0, s15, 0xc000
	ds_read_b128 v[158:161], v153
	ds_read_b128 v[162:165], v153 offset:1024
	ds_read_b128 v[166:169], v153 offset:2048
	ds_read_b128 v[170:173], v153 offset:3072
	ds_read_b128 v[174:177], v153 offset:4096
	ds_read_b128 v[178:181], v153 offset:5120
	ds_read_b128 v[182:185], v153 offset:6144
	ds_read_b128 v[186:189], v153 offset:7168
	global_load_lds_dwordx4 v[190:191], off
	v_lshl_add_u64 v[190:191], s[22:23], 0, v[144:145]
	s_add_i32 m0, s15, 0xe000
	s_nop 0
	global_load_lds_dwordx4 v[190:191], off
	s_waitcnt lgkmcnt(8)
	s_barrier
	s_waitcnt lgkmcnt(0)
	s_setprio 1
	s_waitcnt lgkmcnt(0)
	v_mfma_f32_16x16x32_bf16 v[132:135], v[120:123], v[158:161], v[132:135]
	v_mfma_f32_16x16x32_bf16 v[128:131], v[146:149], v[158:161], v[128:131]
	v_mfma_f32_16x16x32_bf16 v[116:119], v[120:123], v[166:169], v[116:119]
	v_mfma_f32_16x16x32_bf16 v[112:115], v[146:149], v[166:169], v[112:115]
	v_mfma_f32_16x16x32_bf16 v[108:111], v[120:123], v[174:177], v[108:111]
	v_mfma_f32_16x16x32_bf16 v[104:107], v[146:149], v[174:177], v[104:107]
	v_mfma_f32_16x16x32_bf16 v[100:103], v[120:123], v[182:185], v[100:103]
	v_mfma_f32_16x16x32_bf16 v[96:99], v[146:149], v[182:185], v[96:99]
	v_mfma_f32_16x16x32_bf16 v[132:135], v[124:127], v[162:165], v[132:135]
	v_mfma_f32_16x16x32_bf16 v[128:131], v[154:157], v[162:165], v[128:131]
	v_mfma_f32_16x16x32_bf16 v[116:119], v[124:127], v[170:173], v[116:119]
	v_mfma_f32_16x16x32_bf16 v[112:115], v[154:157], v[170:173], v[112:115]
	v_mfma_f32_16x16x32_bf16 v[108:111], v[124:127], v[178:181], v[108:111]
	v_mfma_f32_16x16x32_bf16 v[104:107], v[154:157], v[178:181], v[104:107]
	v_mfma_f32_16x16x32_bf16 v[100:103], v[124:127], v[186:189], v[100:103]
	v_mfma_f32_16x16x32_bf16 v[96:99], v[154:157], v[186:189], v[96:99]
	s_setprio 0
	s_barrier
	s_add_i32 s54, 0, 0x14000
	v_add_u32_e32 v190, s54, v151
	s_add_i32 s51, s51, s38
	ds_read_b128 v[194:197], v190
	ds_read_b128 v[200:203], v190 offset:1024
	ds_read_b128 v[204:207], v190 offset:2048
	ds_read_b128 v[208:211], v190 offset:3072
	v_lshl_add_u64 v[190:191], s[24:25], 0, v[192:193]
	s_mov_b32 m0, s51
	v_lshl_add_u64 v[212:213], s[24:25], 0, v[140:141]
	global_load_lds_dwordx4 v[190:191], off
	s_add_i32 m0, s51, 0x2000
	s_nop 0
	global_load_lds_dwordx4 v[212:213], off
	s_barrier
	s_waitcnt lgkmcnt(0)
	s_setprio 1
	s_waitcnt lgkmcnt(0)
	v_mfma_f32_16x16x32_bf16 v[60:63], v[194:197], v[158:161], v[60:63]
	v_mfma_f32_16x16x32_bf16 v[56:59], v[204:207], v[158:161], v[56:59]
	v_mfma_f32_16x16x32_bf16 v[52:55], v[194:197], v[166:169], v[52:55]
	v_mfma_f32_16x16x32_bf16 v[48:51], v[204:207], v[166:169], v[48:51]
	v_mfma_f32_16x16x32_bf16 v[44:47], v[194:197], v[174:177], v[44:47]
	v_mfma_f32_16x16x32_bf16 v[40:43], v[204:207], v[174:177], v[40:43]
	v_mfma_f32_16x16x32_bf16 v[36:39], v[194:197], v[182:185], v[36:39]
	v_mfma_f32_16x16x32_bf16 v[32:35], v[204:207], v[182:185], v[32:35]
	v_mfma_f32_16x16x32_bf16 v[60:63], v[200:203], v[162:165], v[60:63]
	v_mfma_f32_16x16x32_bf16 v[56:59], v[208:211], v[162:165], v[56:59]
	v_mfma_f32_16x16x32_bf16 v[52:55], v[200:203], v[170:173], v[52:55]
	v_mfma_f32_16x16x32_bf16 v[48:51], v[208:211], v[170:173], v[48:51]
	v_mfma_f32_16x16x32_bf16 v[44:47], v[200:203], v[178:181], v[44:47]
	v_mfma_f32_16x16x32_bf16 v[40:43], v[208:211], v[178:181], v[40:43]
	v_mfma_f32_16x16x32_bf16 v[36:39], v[200:203], v[186:189], v[36:39]
	v_mfma_f32_16x16x32_bf16 v[32:35], v[208:211], v[186:189], v[32:35]
	s_setprio 0
	s_mov_b32 m0, s15
	v_lshl_add_u64 v[214:215], s[26:27], 0, v[136:137]
	s_barrier
	ds_read_b128 v[158:161], v153 offset:16384
	ds_read_b128 v[162:165], v153 offset:17408
	ds_read_b128 v[166:169], v153 offset:18432
	ds_read_b128 v[170:173], v153 offset:19456
	ds_read_b128 v[174:177], v153 offset:20480
	ds_read_b128 v[178:181], v153 offset:21504
	ds_read_b128 v[182:185], v153 offset:22528
	ds_read_b128 v[186:189], v153 offset:23552
	global_load_lds_dwordx4 v[214:215], off
	v_lshl_add_u64 v[216:217], s[26:27], 0, v[138:139]
	s_mov_b32 m0, s39
	s_nop 0
	global_load_lds_dwordx4 v[216:217], off
	s_barrier
	s_waitcnt lgkmcnt(0)
	s_setprio 1
	s_waitcnt lgkmcnt(0)
	v_mfma_f32_16x16x32_bf16 v[92:95], v[120:123], v[158:161], v[92:95]
	v_mfma_f32_16x16x32_bf16 v[88:91], v[146:149], v[158:161], v[88:91]
	v_mfma_f32_16x16x32_bf16 v[84:87], v[120:123], v[166:169], v[84:87]
	v_mfma_f32_16x16x32_bf16 v[80:83], v[146:149], v[166:169], v[80:83]
	v_mfma_f32_16x16x32_bf16 v[76:79], v[120:123], v[174:177], v[76:79]
	v_mfma_f32_16x16x32_bf16 v[72:75], v[146:149], v[174:177], v[72:75]
	v_mfma_f32_16x16x32_bf16 v[68:71], v[120:123], v[182:185], v[68:71]
	v_mfma_f32_16x16x32_bf16 v[64:67], v[146:149], v[182:185], v[64:67]
	v_mfma_f32_16x16x32_bf16 v[92:95], v[124:127], v[162:165], v[92:95]
	v_mfma_f32_16x16x32_bf16 v[88:91], v[154:157], v[162:165], v[88:91]
	v_mfma_f32_16x16x32_bf16 v[84:87], v[124:127], v[170:173], v[84:87]
	v_mfma_f32_16x16x32_bf16 v[80:83], v[154:157], v[170:173], v[80:83]
	v_mfma_f32_16x16x32_bf16 v[76:79], v[124:127], v[178:181], v[76:79]
	v_mfma_f32_16x16x32_bf16 v[72:75], v[154:157], v[178:181], v[72:75]
	v_mfma_f32_16x16x32_bf16 v[68:71], v[124:127], v[186:189], v[68:71]
	v_mfma_f32_16x16x32_bf16 v[64:67], v[154:157], v[186:189], v[64:67]
	s_setprio 0
	s_barrier
; #define PG8_STAGE(bufoff, gbase, voff) do { _Pragma("unroll") for (int _i = 0; _i < 2; ++_i) \
;         __builtin_amdgcn_global_load_lds((const unsigned*)((const char*)(gbase) + (voff)[_i]), (PG8_LAS unsigned*)(lds + (bufoff) + ldsw + _i * 8192), 16, 0, 0); } while (0)
; #define PG8_LDA(dst, b, h) do { _Pragma("unroll") for (int m = 0; m < 4; ++m) _Pragma("unroll") for (int k = 0; k < 2; ++k) dst[m][k] = *(const PG8_LAS bf16x8*)(lds + PG8_SA(b, h) + aoff + m * 2048 + k * 1024); } while (0)
; #define PG8_LDB(dst, b, h) do { _Pragma("unroll") for (int n = 0; n < 2; ++n) _Pragma("unroll") for (int k = 0; k < 2; ++k) dst[n][k] = *(const PG8_LAS bf16x8*)(lds + PG8_SB(b, h) + boff + n * 2048 + k * 1024); } while (0)
; #define PG8_MMA(ai, bj, At, Bt) do { __builtin_amdgcn_s_setprio(1); _Pragma("unroll") for (int m = 0; m < 4; ++m) _Pragma("unroll") for (int n = 0; n < 2; ++n) _Pragma("unroll") for (int k = 0; k < 2; ++k) \
;         acc[ai][bj][m][n] = __builtin_amdgcn_mfma_f32_16x16x32_bf16(Bt[n][k], At[m][k], acc[ai][bj][m][n], 0, 0, 0); __builtin_amdgcn_s_setprio(0); } while (0)
; #define PG8_WAIT_V(n) asm volatile("s_waitcnt vmcnt(" #n ")" ::: "memory")
; #define PG8_WAIT_L(n) asm volatile("s_waitcnt lgkmcnt(" #n ")" ::: "memory")
; #define PG8_BAR __builtin_amdgcn_s_barrier()
; #define PG8_SCHED __builtin_amdgcn_sched_barrier(0)
; template <class Epi, class Sched>
; __device__ __forceinline__ void gemm_phase(PG8_LAS unsigned char* lds, const Gemm g, const Sched& S, const Epi& E, int tid_in) {
;     ...
;             PG8_STAGE(PG8_SB(0, 1), b2 + hstep, voffB);
;             PG8_WAIT_V(6); PG8_BAR; PG8_MMA(1, 1, At, B1); PG8_BAR;
;             PG8_LDB(B0, 1, 0); PG8_SCHED; PG8_LDA(At, 1, 0); PG8_STAGE(PG8_SA(0, 1), a2 + hstep, voffA);
;             PG8_WAIT_L(8); PG8_BAR; PG8_WAIT_L(0); PG8_MMA(0, 0, At, B0); PG8_BAR; PG8_SCHED;
;             PG8_LDB(B1, 1, 1); PG8_STAGE(PG8_SB(1, 0), b3, voffB);
;             PG8_BAR; PG8_WAIT_L(0); PG8_MMA(0, 1, At, B1); PG8_BAR;
;             PG8_LDA(At, 1, 1); PG8_STAGE(PG8_SA(1, 0), a3, voffA);
	s_add_u32 s52, s24, 0x40000
	s_addc_u32 s53, s25, 0
	s_add_i32 s51, s54, s38
	v_lshl_add_u64 v[120:121], s[52:53], 0, v[192:193]
	s_mov_b32 m0, s51
	s_nop 0
	global_load_lds_dwordx4 v[120:121], off
	v_lshl_add_u64 v[120:121], s[52:53], 0, v[140:141]
	s_add_i32 m0, s51, 0x2000
	s_nop 0
	global_load_lds_dwordx4 v[120:121], off
	s_waitcnt vmcnt(6)
	s_barrier
	s_setprio 1
	v_mfma_f32_16x16x32_bf16 v[28:31], v[194:197], v[158:161], v[28:31]
	v_mfma_f32_16x16x32_bf16 v[24:27], v[204:207], v[158:161], v[24:27]
	v_mfma_f32_16x16x32_bf16 v[20:23], v[194:197], v[166:169], v[20:23]
	v_mfma_f32_16x16x32_bf16 v[16:19], v[204:207], v[166:169], v[16:19]
	v_mfma_f32_16x16x32_bf16 v[12:15], v[194:197], v[174:177], v[12:15]
	v_mfma_f32_16x16x32_bf16 v[8:11], v[204:207], v[174:177], v[8:11]
	v_mfma_f32_16x16x32_bf16 v[4:7], v[194:197], v[182:185], v[4:7]
	v_mfma_f32_16x16x32_bf16 v[0:3], v[204:207], v[182:185], v[0:3]
	v_mfma_f32_16x16x32_bf16 v[28:31], v[200:203], v[162:165], v[28:31]
	v_mfma_f32_16x16x32_bf16 v[24:27], v[208:211], v[162:165], v[24:27]
	v_mfma_f32_16x16x32_bf16 v[20:23], v[200:203], v[170:173], v[20:23]
	v_mfma_f32_16x16x32_bf16 v[16:19], v[208:211], v[170:173], v[16:19]
	v_mfma_f32_16x16x32_bf16 v[12:15], v[200:203], v[178:181], v[12:15]
	v_mfma_f32_16x16x32_bf16 v[8:11], v[208:211], v[178:181], v[8:11]
	v_mfma_f32_16x16x32_bf16 v[4:7], v[200:203], v[186:189], v[4:7]
	v_mfma_f32_16x16x32_bf16 v[0:3], v[208:211], v[186:189], v[0:3]
	s_setprio 0
	s_add_i32 s51, 0, 0x18000
	v_add_u32_e32 v154, s51, v151
	s_barrier
	ds_read_b128 v[120:123], v154
	ds_read_b128 v[124:127], v154 offset:1024
	ds_read_b128 v[146:149], v154 offset:2048
	ds_read_b128 v[154:157], v154 offset:3072
	s_add_u32 s26, s26, 0x40000
	s_addc_u32 s27, s27, 0
	s_mov_b32 m0, s40
	v_lshl_add_u64 v[194:195], s[26:27], 0, v[136:137]
	ds_read_b128 v[158:161], v153 offset:32768
	ds_read_b128 v[162:165], v153 offset:33792
	ds_read_b128 v[166:169], v153 offset:34816
	ds_read_b128 v[170:173], v153 offset:35840
	ds_read_b128 v[174:177], v153 offset:36864
	ds_read_b128 v[178:181], v153 offset:37888
	ds_read_b128 v[182:185], v153 offset:38912
	ds_read_b128 v[186:189], v153 offset:39936
	global_load_lds_dwordx4 v[194:195], off
	v_lshl_add_u64 v[194:195], s[26:27], 0, v[138:139]
	s_mov_b32 m0, s41
	s_nop 0
	global_load_lds_dwordx4 v[194:195], off
	s_waitcnt lgkmcnt(8)
	s_barrier
	s_waitcnt lgkmcnt(0)
	s_setprio 1
	s_waitcnt lgkmcnt(0)
	v_mfma_f32_16x16x32_bf16 v[132:135], v[120:123], v[158:161], v[132:135]
	v_mfma_f32_16x16x32_bf16 v[128:131], v[146:149], v[158:161], v[128:131]
	v_mfma_f32_16x16x32_bf16 v[116:119], v[120:123], v[166:169], v[116:119]
	v_mfma_f32_16x16x32_bf16 v[112:115], v[146:149], v[166:169], v[112:115]
	v_mfma_f32_16x16x32_bf16 v[108:111], v[120:123], v[174:177], v[108:111]
	v_mfma_f32_16x16x32_bf16 v[104:107], v[146:149], v[174:177], v[104:107]
	v_mfma_f32_16x16x32_bf16 v[100:103], v[120:123], v[182:185], v[100:103]
	v_mfma_f32_16x16x32_bf16 v[96:99], v[146:149], v[182:185], v[96:99]
	v_mfma_f32_16x16x32_bf16 v[132:135], v[124:127], v[162:165], v[132:135]
	v_mfma_f32_16x16x32_bf16 v[128:131], v[154:157], v[162:165], v[128:131]
	v_mfma_f32_16x16x32_bf16 v[116:119], v[124:127], v[170:173], v[116:119]
	v_mfma_f32_16x16x32_bf16 v[112:115], v[154:157], v[170:173], v[112:115]
	v_mfma_f32_16x16x32_bf16 v[108:111], v[124:127], v[178:181], v[108:111]
	v_mfma_f32_16x16x32_bf16 v[104:107], v[154:157], v[178:181], v[104:107]
	v_mfma_f32_16x16x32_bf16 v[100:103], v[124:127], v[186:189], v[100:103]
	v_mfma_f32_16x16x32_bf16 v[96:99], v[154:157], v[186:189], v[96:99]
	s_setprio 0
	s_barrier
	s_add_i32 s26, 0, 0x1c000
	s_add_i32 s27, s51, s38
	v_add_u32_e32 v199, s26, v151
	v_lshl_add_u64 v[190:191], v[190:191], 0, s[74:75]
	s_mov_b32 m0, s27
	ds_read_b128 v[194:197], v199
	ds_read_b128 v[200:203], v199 offset:1024
	ds_read_b128 v[204:207], v199 offset:2048
	ds_read_b128 v[208:211], v199 offset:3072
	global_load_lds_dwordx4 v[190:191], off
	v_lshl_add_u64 v[190:191], v[212:213], 0, s[74:75]
	s_add_i32 m0, s27, 0x2000
	s_nop 0
	global_load_lds_dwordx4 v[190:191], off
	s_barrier
	s_waitcnt lgkmcnt(0)
	s_setprio 1
	s_waitcnt lgkmcnt(0)
	v_mfma_f32_16x16x32_bf16 v[60:63], v[194:197], v[158:161], v[60:63]
	v_mfma_f32_16x16x32_bf16 v[56:59], v[204:207], v[158:161], v[56:59]
	v_mfma_f32_16x16x32_bf16 v[52:55], v[194:197], v[166:169], v[52:55]
	v_mfma_f32_16x16x32_bf16 v[48:51], v[204:207], v[166:169], v[48:51]
	v_mfma_f32_16x16x32_bf16 v[44:47], v[194:197], v[174:177], v[44:47]
	v_mfma_f32_16x16x32_bf16 v[40:43], v[204:207], v[174:177], v[40:43]
	v_mfma_f32_16x16x32_bf16 v[36:39], v[194:197], v[182:185], v[36:39]
	v_mfma_f32_16x16x32_bf16 v[32:35], v[204:207], v[182:185], v[32:35]
	v_mfma_f32_16x16x32_bf16 v[60:63], v[200:203], v[162:165], v[60:63]
	v_mfma_f32_16x16x32_bf16 v[56:59], v[208:211], v[162:165], v[56:59]
	v_mfma_f32_16x16x32_bf16 v[52:55], v[200:203], v[170:173], v[52:55]
	v_mfma_f32_16x16x32_bf16 v[48:51], v[208:211], v[170:173], v[48:51]
	v_mfma_f32_16x16x32_bf16 v[44:47], v[200:203], v[178:181], v[44:47]
	v_mfma_f32_16x16x32_bf16 v[40:43], v[208:211], v[178:181], v[40:43]
	v_mfma_f32_16x16x32_bf16 v[36:39], v[200:203], v[186:189], v[36:39]
	v_mfma_f32_16x16x32_bf16 v[32:35], v[208:211], v[186:189], v[32:35]
	s_setprio 0
	s_mov_b32 m0, s42
	v_lshl_add_u64 v[190:191], v[214:215], 0, s[74:75]
	s_barrier
	ds_read_b128 v[158:161], v153 offset:49152
	ds_read_b128 v[162:165], v153 offset:50176
	ds_read_b128 v[166:169], v153 offset:51200
	ds_read_b128 v[170:173], v153 offset:52224
	ds_read_b128 v[174:177], v153 offset:53248
	ds_read_b128 v[178:181], v153 offset:54272
	ds_read_b128 v[182:185], v153 offset:55296
	ds_read_b128 v[186:189], v153 offset:56320
	global_load_lds_dwordx4 v[190:191], off
	v_lshl_add_u64 v[190:191], v[216:217], 0, s[74:75]
	s_mov_b32 m0, s43
	s_nop 0
	global_load_lds_dwordx4 v[190:191], off
	s_barrier
; __device__ __forceinline__ unsigned cvt_pk_bf16(float lo, float hi) { unsigned r; asm volatile("s_nop 0\n\tv_cvt_pk_bf16_f32 %0, %1, %2\n\ts_nop 1" : "=v"(r) : "v"(lo), "v"(hi)); return r; }
; #define PG8_STAGE(bufoff, gbase, voff) do { _Pragma("unroll") for (int _i = 0; _i < 2; ++_i) \
;         __builtin_amdgcn_global_load_lds((const unsigned*)((const char*)(gbase) + (voff)[_i]), (PG8_LAS unsigned*)(lds + (bufoff) + ldsw + _i * 8192), 16, 0, 0); } while (0)
; #define PG8_MMA(ai, bj, At, Bt) do { __builtin_amdgcn_s_setprio(1); _Pragma("unroll") for (int m = 0; m < 4; ++m) _Pragma("unroll") for (int n = 0; n < 2; ++n) _Pragma("unroll") for (int k = 0; k < 2; ++k) \
;         acc[ai][bj][m][n] = __builtin_amdgcn_mfma_f32_16x16x32_bf16(Bt[n][k], At[m][k], acc[ai][bj][m][n], 0, 0, 0); __builtin_amdgcn_s_setprio(0); } while (0)
; #define PG8_WAIT_V(n) asm volatile("s_waitcnt vmcnt(" #n ")" ::: "memory")
; #define PG8_WAIT_L(n) asm volatile("s_waitcnt lgkmcnt(" #n ")" ::: "memory")
; template <class Epi, class Sched>
; __device__ __forceinline__ void gemm_phase(PG8_LAS unsigned char* lds, const Gemm g, const Sched& S, const Epi& E, int tid_in) {
;     ...
;             PG8_BAR; PG8_WAIT_L(0); PG8_MMA(1, 0, At, B0); PG8_BAR; PG8_SCHED;
;             PG8_STAGE(PG8_SB(1, 1), b3 + hstep, voffB);
;             PG8_WAIT_V(6); PG8_BAR; PG8_MMA(1, 1, At, B1); PG8_BAR;
;     __device__ __forceinline__ void operator()(f32x4 (&acc)[2][2][4][2], const Unit& u, int wr, int wc, int fr, int fq) const {
;         const int row0 = u.pm * 256 + wr * 64 + fr, col0 = u.pn * 256 + wc * 32 + 8 * fq;
; #pragma unroll
;         for (int bj = 0; bj < 2; ++bj) { const f32x4 b0 = *(const f32x4*)(bias + col0 + bj * 128), b1 = *(const f32x4*)(bias + col0 + bj * 128 + 4);
; #pragma unroll
;             for (int ai = 0; ai < 2; ++ai)
; #pragma unroll
;                 for (int m = 0; m < 4; ++m) { f32x4 v0 = acc[ai][bj][m][0] + b0, v1 = acc[ai][bj][m][1] + b1;
; #pragma unroll
;                     for (int j = 0; j < 4; ++j) { v0[j] = fmaxf(v0[j], 0.f); v0[j] *= v0[j]; v1[j] = fmaxf(v1[j], 0.f); v1[j] *= v1[j]; }
;                     u32x4 w; w.x = cvt_pk_bf16(v0[0], v0[1]); w.y = cvt_pk_bf16(v0[2], v0[3]); w.z = cvt_pk_bf16(v1[0], v1[1]); w.w = cvt_pk_bf16(v1[2], v1[3]);
;                     *(u32x4*)(O + (size_t)(row0 + ai * 128 + m * 16) * 4096 + col0 + bj * 128) = w; } }
	s_waitcnt lgkmcnt(0)
	s_setprio 1
	s_waitcnt lgkmcnt(0)
	v_mfma_f32_16x16x32_bf16 v[92:95], v[120:123], v[158:161], v[92:95]
	v_mfma_f32_16x16x32_bf16 v[88:91], v[146:149], v[158:161], v[88:91]
	v_mfma_f32_16x16x32_bf16 v[84:87], v[120:123], v[166:169], v[84:87]
	v_mfma_f32_16x16x32_bf16 v[80:83], v[146:149], v[166:169], v[80:83]
	v_mfma_f32_16x16x32_bf16 v[76:79], v[120:123], v[174:177], v[76:79]
	v_mfma_f32_16x16x32_bf16 v[72:75], v[146:149], v[174:177], v[72:75]
	v_mfma_f32_16x16x32_bf16 v[68:71], v[120:123], v[182:185], v[68:71]
	v_mfma_f32_16x16x32_bf16 v[64:67], v[146:149], v[182:185], v[64:67]
	v_mfma_f32_16x16x32_bf16 v[92:95], v[124:127], v[162:165], v[92:95]
	v_mfma_f32_16x16x32_bf16 v[88:91], v[154:157], v[162:165], v[88:91]
	v_mfma_f32_16x16x32_bf16 v[84:87], v[124:127], v[170:173], v[84:87]
	v_mfma_f32_16x16x32_bf16 v[80:83], v[154:157], v[170:173], v[80:83]
	v_mfma_f32_16x16x32_bf16 v[76:79], v[124:127], v[178:181], v[76:79]
	v_mfma_f32_16x16x32_bf16 v[72:75], v[154:157], v[178:181], v[72:75]
	v_mfma_f32_16x16x32_bf16 v[68:71], v[124:127], v[186:189], v[68:71]
	v_mfma_f32_16x16x32_bf16 v[64:67], v[154:157], v[186:189], v[64:67]
	s_setprio 0
	s_barrier
	s_add_u32 s24, s24, 0x40080
	s_addc_u32 s25, s25, 0
	s_add_i32 s26, s26, s38
	v_lshl_add_u64 v[120:121], s[24:25], 0, v[192:193]
	s_mov_b32 m0, s26
	s_nop 0
	global_load_lds_dwordx4 v[120:121], off
	v_lshl_add_u64 v[120:121], s[24:25], 0, v[140:141]
	s_add_i32 m0, s26, 0x2000
	s_nop 0
	global_load_lds_dwordx4 v[120:121], off
	s_waitcnt vmcnt(6)
	s_barrier
	s_setprio 1
	v_mfma_f32_16x16x32_bf16 v[28:31], v[194:197], v[158:161], v[28:31]
	v_mfma_f32_16x16x32_bf16 v[24:27], v[204:207], v[158:161], v[24:27]
	v_mfma_f32_16x16x32_bf16 v[20:23], v[194:197], v[166:169], v[20:23]
	v_mfma_f32_16x16x32_bf16 v[16:19], v[204:207], v[166:169], v[16:19]
	v_mfma_f32_16x16x32_bf16 v[12:15], v[194:197], v[174:177], v[12:15]
	v_mfma_f32_16x16x32_bf16 v[8:11], v[204:207], v[174:177], v[8:11]
	v_mfma_f32_16x16x32_bf16 v[4:7], v[194:197], v[182:185], v[4:7]
	v_mfma_f32_16x16x32_bf16 v[0:3], v[204:207], v[182:185], v[0:3]
	v_mfma_f32_16x16x32_bf16 v[28:31], v[200:203], v[162:165], v[28:31]
	v_mfma_f32_16x16x32_bf16 v[24:27], v[208:211], v[162:165], v[24:27]
	v_mfma_f32_16x16x32_bf16 v[20:23], v[200:203], v[170:173], v[20:23]
	v_mfma_f32_16x16x32_bf16 v[16:19], v[208:211], v[170:173], v[16:19]
	v_mfma_f32_16x16x32_bf16 v[12:15], v[200:203], v[178:181], v[12:15]
	v_mfma_f32_16x16x32_bf16 v[8:11], v[208:211], v[178:181], v[8:11]
	v_mfma_f32_16x16x32_bf16 v[4:7], v[200:203], v[186:189], v[4:7]
	v_mfma_f32_16x16x32_bf16 v[0:3], v[208:211], v[186:189], v[0:3]
	s_setprio 0
	s_add_i32 s50, s50, 2
	s_add_u32 s22, s22, 0x100
	s_addc_u32 s23, s23, 0
	s_add_u32 s48, s48, 0x100
	s_addc_u32 s49, s49, 0
	s_cmp_gt_u32 s50, 13
	s_barrier
	s_cbranch_scc0 .LBB0_295
	v_lshl_or_b32 v154, s33, 8, v152
	v_ashrrev_i32_e32 v155, 31, v154
	v_lshl_add_u64 v[146:147], v[154:155], 2, s[6:7]
	global_load_dwordx4 v[120:123], v[146:147], off offset:16
	global_load_dwordx4 v[124:127], v[146:147], off
	global_load_dwordx4 v[200:203], v[146:147], off offset:528
	global_load_dwordx4 v[204:207], v[146:147], off offset:512
	v_lshl_add_u32 v148, s14, 8, v150
	v_ashrrev_i32_e32 v149, 31, v148
	s_mov_b32 s5, 0x100000
	s_mov_b64 s[22:23], 0x100000
	s_mov_b32 s33, s4
	s_mov_b32 s14, s8
	s_mov_b64 s[24:25], s[12:13]
	s_waitcnt vmcnt(0)
	v_pk_add_f32 v[128:129], v[128:129], v[120:121]
	v_pk_add_f32 v[134:135], v[134:135], v[126:127]
	v_pk_add_f32 v[132:133], v[132:133], v[124:125]
	v_pk_add_f32 v[130:131], v[130:131], v[122:123]
	v_max_f32_e32 v132, 0, v132
	v_max_f32_e32 v128, 0, v128
	v_max_f32_e32 v133, 0, v133
	v_max_f32_e32 v129, 0, v129
	v_max_f32_e32 v134, 0, v134
	v_mul_f32_e32 v132, v132, v132
	v_mul_f32_e32 v128, v128, v128
	v_mul_f32_e32 v133, v133, v133
	v_mul_f32_e32 v129, v129, v129
	v_mul_f32_e32 v134, v134, v134
	v_max_f32_e32 v130, 0, v130
	v_max_f32_e32 v135, 0, v135
	v_max_f32_e32 v131, 0, v131
	v_mul_f32_e32 v130, v130, v130
	v_mul_f32_e32 v135, v135, v135
	v_mul_f32_e32 v131, v131, v131
	v_cvt_pk_bf16_f32 v132, v132, v133
	v_cvt_pk_bf16_f32 v133, v134, v135
	v_cvt_pk_bf16_f32 v134, v128, v129
	v_lshlrev_b64 v[128:129], 13, v[148:149]
	v_cvt_pk_bf16_f32 v135, v130, v131
	v_lshl_add_u64 v[128:129], s[0:1], 0, v[128:129]
	v_lshlrev_b64 v[130:131], 1, v[154:155]
	v_pk_add_f32 v[114:115], v[114:115], v[122:123]
	v_lshl_add_u64 v[128:129], v[128:129], 0, v[130:131]
	v_pk_add_f32 v[118:119], v[118:119], v[126:127]
	v_pk_add_f32 v[116:117], v[116:117], v[124:125]
	v_pk_add_f32 v[112:113], v[112:113], v[120:121]
	v_max_f32_e32 v114, 0, v114
	global_store_dwordx4 v[128:129], v[132:135], off
	v_max_f32_e32 v116, 0, v116
	v_max_f32_e32 v112, 0, v112
	v_mul_f32_e32 v132, v114, v114
	v_max_f32_e32 v114, 0, v119
	v_mul_f32_e32 v116, v116, v116
	v_mul_f32_e32 v112, v112, v112
	v_max_f32_e32 v117, 0, v117
	v_max_f32_e32 v113, 0, v113
	v_max_f32_e32 v118, 0, v118
	v_mul_f32_e32 v119, v114, v114
	v_max_f32_e32 v114, 0, v115
	v_mul_f32_e32 v117, v117, v117
	v_mul_f32_e32 v113, v113, v113
	v_mul_f32_e32 v118, v118, v118
	v_mul_f32_e32 v133, v114, v114
	v_cvt_pk_bf16_f32 v114, v116, v117
	v_cvt_pk_bf16_f32 v115, v118, v119
	v_cvt_pk_bf16_f32 v116, v112, v113
	v_or_b32_e32 v112, 16, v148
	v_ashrrev_i32_e32 v113, 31, v112
	v_lshlrev_b64 v[112:113], 13, v[112:113]
	v_lshl_add_u64 v[112:113], s[0:1], 0, v[112:113]
	v_pk_add_f32 v[106:107], v[106:107], v[122:123]
	v_lshl_add_u64 v[112:113], v[112:113], 0, v[130:131]
	v_pk_add_f32 v[110:111], v[110:111], v[126:127]
	v_pk_add_f32 v[108:109], v[108:109], v[124:125]
	v_pk_add_f32 v[104:105], v[104:105], v[120:121]
; __device__ __forceinline__ unsigned cvt_pk_bf16(float lo, float hi) { unsigned r; asm volatile("s_nop 0\n\tv_cvt_pk_bf16_f32 %0, %1, %2\n\ts_nop 1" : "=v"(r) : "v"(lo), "v"(hi)); return r; }
;     __device__ __forceinline__ void operator()(f32x4 (&acc)[2][2][4][2], const Unit& u, int wr, int wc, int fr, int fq) const {
;         const int row0 = u.pm * 256 + wr * 64 + fr, col0 = u.pn * 256 + wc * 32 + 8 * fq;
; #pragma unroll
;         for (int bj = 0; bj < 2; ++bj) { const f32x4 b0 = *(const f32x4*)(bias + col0 + bj * 128), b1 = *(const f32x4*)(bias + col0 + bj * 128 + 4);
; #pragma unroll
;             for (int ai = 0; ai < 2; ++ai)
; #pragma unroll
;                 for (int m = 0; m < 4; ++m) { f32x4 v0 = acc[ai][bj][m][0] + b0, v1 = acc[ai][bj][m][1] + b1;
; #pragma unroll
;                     for (int j = 0; j < 4; ++j) { v0[j] = fmaxf(v0[j], 0.f); v0[j] *= v0[j]; v1[j] = fmaxf(v1[j], 0.f); v1[j] *= v1[j]; }
;                     u32x4 w; w.x = cvt_pk_bf16(v0[0], v0[1]); w.y = cvt_pk_bf16(v0[2], v0[3]); w.z = cvt_pk_bf16(v1[0], v1[1]); w.w = cvt_pk_bf16(v1[2], v1[3]);
;                     *(u32x4*)(O + (size_t)(row0 + ai * 128 + m * 16) * 4096 + col0 + bj * 128) = w; } }
	v_max_f32_e32 v106, 0, v106
	v_cvt_pk_bf16_f32 v117, v132, v133
	global_store_dwordx4 v[112:113], v[114:117], off
	v_max_f32_e32 v108, 0, v108
	v_max_f32_e32 v104, 0, v104
	v_mul_f32_e32 v114, v106, v106
	v_max_f32_e32 v106, 0, v111
	v_mul_f32_e32 v108, v108, v108
	v_mul_f32_e32 v104, v104, v104
	v_max_f32_e32 v109, 0, v109
	v_max_f32_e32 v105, 0, v105
	v_max_f32_e32 v110, 0, v110
	v_mul_f32_e32 v111, v106, v106
	v_max_f32_e32 v106, 0, v107
	v_mul_f32_e32 v109, v109, v109
	v_mul_f32_e32 v105, v105, v105
	v_mul_f32_e32 v110, v110, v110
	v_mul_f32_e32 v115, v106, v106
	v_cvt_pk_bf16_f32 v106, v108, v109
	v_cvt_pk_bf16_f32 v107, v110, v111
	v_cvt_pk_bf16_f32 v108, v104, v105
	v_or_b32_e32 v104, 32, v148
	v_ashrrev_i32_e32 v105, 31, v104
	v_lshlrev_b64 v[104:105], 13, v[104:105]
	v_lshl_add_u64 v[104:105], s[0:1], 0, v[104:105]
	v_pk_add_f32 v[98:99], v[98:99], v[122:123]
	v_lshl_add_u64 v[104:105], v[104:105], 0, v[130:131]
	v_pk_add_f32 v[102:103], v[102:103], v[126:127]
	v_pk_add_f32 v[100:101], v[100:101], v[124:125]
	v_pk_add_f32 v[96:97], v[96:97], v[120:121]
	v_max_f32_e32 v98, 0, v98
	v_cvt_pk_bf16_f32 v109, v114, v115
	global_store_dwordx4 v[104:105], v[106:109], off
	v_max_f32_e32 v100, 0, v100
	v_max_f32_e32 v96, 0, v96
	v_mul_f32_e32 v106, v98, v98
	v_max_f32_e32 v98, 0, v103
	v_mul_f32_e32 v100, v100, v100
	v_mul_f32_e32 v96, v96, v96
	v_max_f32_e32 v101, 0, v101
	v_max_f32_e32 v97, 0, v97
	v_max_f32_e32 v102, 0, v102
	v_mul_f32_e32 v103, v98, v98
	v_max_f32_e32 v98, 0, v99
	v_mul_f32_e32 v101, v101, v101
	v_mul_f32_e32 v97, v97, v97
	v_mul_f32_e32 v102, v102, v102
	v_mul_f32_e32 v107, v98, v98
	v_cvt_pk_bf16_f32 v98, v100, v101
	v_cvt_pk_bf16_f32 v99, v102, v103
	v_cvt_pk_bf16_f32 v100, v96, v97
	v_or_b32_e32 v96, 48, v148
	v_ashrrev_i32_e32 v97, 31, v96
	v_lshlrev_b64 v[96:97], 13, v[96:97]
	v_lshl_add_u64 v[96:97], s[0:1], 0, v[96:97]
	v_pk_add_f32 v[90:91], v[90:91], v[122:123]
	v_lshl_add_u64 v[96:97], v[96:97], 0, v[130:131]
	v_pk_add_f32 v[94:95], v[94:95], v[126:127]
	v_max_f32_e32 v90, 0, v90
	v_cvt_pk_bf16_f32 v101, v106, v107
	global_store_dwordx4 v[96:97], v[98:101], off
	v_pk_add_f32 v[92:93], v[92:93], v[124:125]
	v_max_f32_e32 v94, 0, v94
	v_mul_f32_e32 v98, v90, v90
	v_max_f32_e32 v90, 0, v95
	v_max_f32_e32 v92, 0, v92
	v_max_f32_e32 v93, 0, v93
	v_mul_f32_e32 v94, v94, v94
	v_mul_f32_e32 v95, v90, v90
	v_max_f32_e32 v90, 0, v91
	v_pk_add_f32 v[88:89], v[88:89], v[120:121]
	v_mul_f32_e32 v92, v92, v92
	v_mul_f32_e32 v93, v93, v93
	v_mul_f32_e32 v99, v90, v90
	v_cvt_pk_bf16_f32 v90, v92, v93
	v_cvt_pk_bf16_f32 v91, v94, v95
	v_add_co_u32_e32 v94, vcc, s5, v128
	v_pk_add_f32 v[82:83], v[82:83], v[122:123]
	v_max_f32_e32 v88, 0, v88
	v_max_f32_e32 v89, 0, v89
	v_addc_co_u32_e32 v95, vcc, 0, v129, vcc
	v_pk_add_f32 v[86:87], v[86:87], v[126:127]
	v_max_f32_e32 v82, 0, v82
	v_mul_f32_e32 v88, v88, v88
	v_mul_f32_e32 v89, v89, v89
	v_cvt_pk_bf16_f32 v92, v88, v89
	v_cvt_pk_bf16_f32 v93, v98, v99
	global_store_dwordx4 v[94:95], v[90:93], off
	v_pk_add_f32 v[84:85], v[84:85], v[124:125]
	v_max_f32_e32 v86, 0, v86
	v_mul_f32_e32 v90, v82, v82
	v_max_f32_e32 v82, 0, v87
	v_max_f32_e32 v84, 0, v84
	v_max_f32_e32 v85, 0, v85
	v_mul_f32_e32 v86, v86, v86
	v_mul_f32_e32 v87, v82, v82
	v_max_f32_e32 v82, 0, v83
	s_mov_b32 s5, 0x120000
	v_pk_add_f32 v[80:81], v[80:81], v[120:121]
	v_mul_f32_e32 v84, v84, v84
	v_mul_f32_e32 v85, v85, v85
	v_mul_f32_e32 v91, v82, v82
	v_cvt_pk_bf16_f32 v82, v84, v85
	v_cvt_pk_bf16_f32 v83, v86, v87
	v_add_co_u32_e32 v86, vcc, s5, v128
	v_pk_add_f32 v[74:75], v[74:75], v[122:123]
	v_max_f32_e32 v80, 0, v80
	v_max_f32_e32 v81, 0, v81
	v_addc_co_u32_e32 v87, vcc, 0, v129, vcc
	v_pk_add_f32 v[78:79], v[78:79], v[126:127]
	v_max_f32_e32 v74, 0, v74
	v_mul_f32_e32 v80, v80, v80
	v_mul_f32_e32 v81, v81, v81
	v_cvt_pk_bf16_f32 v84, v80, v81
	v_cvt_pk_bf16_f32 v85, v90, v91
	global_store_dwordx4 v[86:87], v[82:85], off
	v_pk_add_f32 v[76:77], v[76:77], v[124:125]
	v_max_f32_e32 v78, 0, v78
	v_mul_f32_e32 v82, v74, v74
	v_max_f32_e32 v74, 0, v79
	v_max_f32_e32 v76, 0, v76
	v_max_f32_e32 v77, 0, v77
	v_mul_f32_e32 v78, v78, v78
	v_mul_f32_e32 v79, v74, v74
	v_max_f32_e32 v74, 0, v75
	s_mov_b32 s5, 0x140000
	v_pk_add_f32 v[72:73], v[72:73], v[120:121]
	v_mul_f32_e32 v76, v76, v76
	v_mul_f32_e32 v77, v77, v77
	v_mul_f32_e32 v83, v74, v74
	v_cvt_pk_bf16_f32 v74, v76, v77
	v_cvt_pk_bf16_f32 v75, v78, v79
	v_add_co_u32_e32 v78, vcc, s5, v128
	v_pk_add_f32 v[64:65], v[64:65], v[120:121]
	v_max_f32_e32 v72, 0, v72
	v_max_f32_e32 v73, 0, v73
	v_addc_co_u32_e32 v79, vcc, 0, v129, vcc
	v_pk_add_f32 v[68:69], v[68:69], v[124:125]
	v_pk_add_f32 v[66:67], v[66:67], v[122:123]
	v_max_f32_e32 v64, 0, v64
	v_mul_f32_e32 v72, v72, v72
	v_mul_f32_e32 v73, v73, v73
	v_cvt_pk_bf16_f32 v76, v72, v73
	v_cvt_pk_bf16_f32 v77, v82, v83
	global_store_dwordx4 v[78:79], v[74:77], off
	v_pk_add_f32 v[70:71], v[70:71], v[126:127]
	v_max_f32_e32 v68, 0, v68
	v_mul_f32_e32 v74, v64, v64
	v_max_f32_e32 v64, 0, v69
	v_max_f32_e32 v65, 0, v65
	v_max_f32_e32 v66, 0, v66
	v_mul_f32_e32 v68, v68, v68
	v_mul_f32_e32 v64, v64, v64
	v_mul_f32_e32 v69, v65, v65
	v_max_f32_e32 v65, 0, v70
	v_mul_f32_e32 v70, v66, v66
	v_max_f32_e32 v66, 0, v71
	s_mov_b32 s5, 0x160000
	v_mul_f32_e32 v65, v65, v65
	v_mul_f32_e32 v66, v66, v66
	v_max_f32_e32 v67, 0, v67
	v_cvt_pk_bf16_f32 v64, v68, v64
	v_add_co_u32_e32 v68, vcc, s5, v128
	v_mul_f32_e32 v67, v67, v67
	v_cvt_pk_bf16_f32 v65, v65, v66
	v_cvt_pk_bf16_f32 v66, v74, v69
	s_nop 0
	v_addc_co_u32_e32 v69, vcc, 0, v129, vcc
	v_cvt_pk_bf16_f32 v67, v70, v67
	global_store_dwordx4 v[68:69], v[64:67], off
	s_nop 1
; __device__ __forceinline__ unsigned cvt_pk_bf16(float lo, float hi) { unsigned r; asm volatile("s_nop 0\n\tv_cvt_pk_bf16_f32 %0, %1, %2\n\ts_nop 1" : "=v"(r) : "v"(lo), "v"(hi)); return r; }
;     __device__ __forceinline__ void operator()(f32x4 (&acc)[2][2][4][2], const Unit& u, int wr, int wc, int fr, int fq) const {
;         const int row0 = u.pm * 256 + wr * 64 + fr, col0 = u.pn * 256 + wc * 32 + 8 * fq;
; #pragma unroll
;         for (int bj = 0; bj < 2; ++bj) { const f32x4 b0 = *(const f32x4*)(bias + col0 + bj * 128), b1 = *(const f32x4*)(bias + col0 + bj * 128 + 4);
; #pragma unroll
;             for (int ai = 0; ai < 2; ++ai)
; #pragma unroll
;                 for (int m = 0; m < 4; ++m) { f32x4 v0 = acc[ai][bj][m][0] + b0, v1 = acc[ai][bj][m][1] + b1;
; #pragma unroll
;                     for (int j = 0; j < 4; ++j) { v0[j] = fmaxf(v0[j], 0.f); v0[j] *= v0[j]; v1[j] = fmaxf(v1[j], 0.f); v1[j] *= v1[j]; }
;                     u32x4 w; w.x = cvt_pk_bf16(v0[0], v0[1]); w.y = cvt_pk_bf16(v0[2], v0[3]); w.z = cvt_pk_bf16(v1[0], v1[1]); w.w = cvt_pk_bf16(v1[2], v1[3]);
;                     *(u32x4*)(O + (size_t)(row0 + ai * 128 + m * 16) * 4096 + col0 + bj * 128) = w; } }
	v_mov_b32_e32 v64, v200
	v_mov_b32_e32 v65, v201
	v_mov_b32_e32 v66, v202
	v_mov_b32_e32 v67, v203
	v_mov_b32_e32 v68, v204
	v_mov_b32_e32 v69, v205
	v_mov_b32_e32 v70, v206
	v_mov_b32_e32 v71, v207
	v_lshl_add_u64 v[88:89], v[128:129], 0, s[22:23]
	s_mov_b64 s[22:23], 0x120000
	v_lshl_add_u64 v[80:81], v[128:129], 0, s[22:23]
	s_mov_b64 s[22:23], 0x140000
	v_lshl_add_u64 v[72:73], v[128:129], 0, s[22:23]
	s_mov_b64 s[22:23], 0x160000
	v_lshl_add_u64 v[74:75], v[128:129], 0, s[22:23]
	s_and_b64 vcc, exec, s[2:3]
	s_mov_b64 s[22:23], s[10:11]
	v_pk_add_f32 v[56:57], v[56:57], v[64:65]
	v_pk_add_f32 v[60:61], v[60:61], v[68:69]
	v_pk_add_f32 v[58:59], v[58:59], v[66:67]
	v_max_f32_e32 v56, 0, v56
	v_pk_add_f32 v[62:63], v[62:63], v[70:71]
	v_mul_f32_e32 v76, v56, v56
	v_max_f32_e32 v56, 0, v61
	v_max_f32_e32 v57, 0, v57
	v_max_f32_e32 v58, 0, v58
	v_max_f32_e32 v60, 0, v60
	v_mul_f32_e32 v56, v56, v56
	v_mul_f32_e32 v61, v57, v57
	v_max_f32_e32 v57, 0, v62
	v_mul_f32_e32 v62, v58, v58
	v_max_f32_e32 v58, 0, v63
	v_max_f32_e32 v59, 0, v59
	v_pk_add_f32 v[48:49], v[48:49], v[64:65]
	v_mul_f32_e32 v60, v60, v60
	v_mul_f32_e32 v57, v57, v57
	v_mul_f32_e32 v58, v58, v58
	v_mul_f32_e32 v59, v59, v59
	v_cvt_pk_bf16_f32 v56, v60, v56
	v_pk_add_f32 v[52:53], v[52:53], v[68:69]
	v_pk_add_f32 v[50:51], v[50:51], v[66:67]
	v_max_f32_e32 v48, 0, v48
	v_cvt_pk_bf16_f32 v57, v57, v58
	v_cvt_pk_bf16_f32 v58, v76, v61
	v_cvt_pk_bf16_f32 v59, v62, v59
	global_store_dwordx4 v[128:129], v[56:59], off offset:256
	v_pk_add_f32 v[54:55], v[54:55], v[70:71]
	v_max_f32_e32 v49, 0, v49
	v_mul_f32_e32 v56, v48, v48
	v_max_f32_e32 v48, 0, v53
	v_max_f32_e32 v50, 0, v50
	v_max_f32_e32 v52, 0, v52
	v_mul_f32_e32 v48, v48, v48
	v_mul_f32_e32 v53, v49, v49
	v_max_f32_e32 v49, 0, v54
	v_mul_f32_e32 v54, v50, v50
	v_max_f32_e32 v50, 0, v55
	v_max_f32_e32 v51, 0, v51
	v_pk_add_f32 v[40:41], v[40:41], v[64:65]
	v_mul_f32_e32 v52, v52, v52
	v_mul_f32_e32 v49, v49, v49
	v_mul_f32_e32 v50, v50, v50
	v_mul_f32_e32 v51, v51, v51
	v_cvt_pk_bf16_f32 v48, v52, v48
	v_pk_add_f32 v[44:45], v[44:45], v[68:69]
	v_pk_add_f32 v[42:43], v[42:43], v[66:67]
	v_max_f32_e32 v40, 0, v40
	v_cvt_pk_bf16_f32 v49, v49, v50
	v_cvt_pk_bf16_f32 v50, v56, v53
	v_cvt_pk_bf16_f32 v51, v54, v51
	global_store_dwordx4 v[112:113], v[48:51], off offset:256
	v_pk_add_f32 v[46:47], v[46:47], v[70:71]
	v_max_f32_e32 v41, 0, v41
	v_mul_f32_e32 v48, v40, v40
	v_max_f32_e32 v40, 0, v45
	v_max_f32_e32 v42, 0, v42
	v_max_f32_e32 v44, 0, v44
	v_mul_f32_e32 v40, v40, v40
	v_mul_f32_e32 v45, v41, v41
	v_max_f32_e32 v41, 0, v46
	v_mul_f32_e32 v46, v42, v42
	v_max_f32_e32 v42, 0, v47
	v_max_f32_e32 v43, 0, v43
	v_pk_add_f32 v[32:33], v[32:33], v[64:65]
	v_mul_f32_e32 v44, v44, v44
	v_mul_f32_e32 v41, v41, v41
	v_mul_f32_e32 v42, v42, v42
	v_mul_f32_e32 v43, v43, v43
	v_cvt_pk_bf16_f32 v40, v44, v40
	v_pk_add_f32 v[36:37], v[36:37], v[68:69]
	v_pk_add_f32 v[34:35], v[34:35], v[66:67]
	v_max_f32_e32 v32, 0, v32
	v_cvt_pk_bf16_f32 v41, v41, v42
	v_cvt_pk_bf16_f32 v42, v48, v45
	v_cvt_pk_bf16_f32 v43, v46, v43
	global_store_dwordx4 v[104:105], v[40:43], off offset:256
	v_pk_add_f32 v[38:39], v[38:39], v[70:71]
	v_max_f32_e32 v33, 0, v33
	v_mul_f32_e32 v40, v32, v32
	v_max_f32_e32 v32, 0, v37
	v_max_f32_e32 v34, 0, v34
	v_max_f32_e32 v36, 0, v36
	v_mul_f32_e32 v32, v32, v32
	v_mul_f32_e32 v37, v33, v33
	v_max_f32_e32 v33, 0, v38
	v_mul_f32_e32 v38, v34, v34
	v_max_f32_e32 v34, 0, v39
	v_max_f32_e32 v35, 0, v35
	v_pk_add_f32 v[24:25], v[24:25], v[64:65]
	v_mul_f32_e32 v36, v36, v36
	v_mul_f32_e32 v33, v33, v33
	v_mul_f32_e32 v34, v34, v34
	v_mul_f32_e32 v35, v35, v35
	v_cvt_pk_bf16_f32 v32, v36, v32
	v_pk_add_f32 v[28:29], v[28:29], v[68:69]
	v_pk_add_f32 v[26:27], v[26:27], v[66:67]
	v_max_f32_e32 v24, 0, v24
	v_cvt_pk_bf16_f32 v33, v33, v34
	v_cvt_pk_bf16_f32 v34, v40, v37
	v_cvt_pk_bf16_f32 v35, v38, v35
	global_store_dwordx4 v[96:97], v[32:35], off offset:256
	v_pk_add_f32 v[30:31], v[30:31], v[70:71]
	v_max_f32_e32 v25, 0, v25
	v_mul_f32_e32 v32, v24, v24
	v_max_f32_e32 v24, 0, v29
	v_max_f32_e32 v26, 0, v26
	v_max_f32_e32 v28, 0, v28
	v_mul_f32_e32 v24, v24, v24
	v_mul_f32_e32 v29, v25, v25
	v_max_f32_e32 v25, 0, v30
	v_mul_f32_e32 v30, v26, v26
	v_max_f32_e32 v26, 0, v31
	v_max_f32_e32 v27, 0, v27
	v_pk_add_f32 v[16:17], v[16:17], v[64:65]
	v_mul_f32_e32 v28, v28, v28
	v_mul_f32_e32 v25, v25, v25
	v_mul_f32_e32 v26, v26, v26
	v_mul_f32_e32 v27, v27, v27
	v_cvt_pk_bf16_f32 v24, v28, v24
	v_pk_add_f32 v[20:21], v[20:21], v[68:69]
	v_pk_add_f32 v[18:19], v[18:19], v[66:67]
	v_max_f32_e32 v16, 0, v16
	v_cvt_pk_bf16_f32 v25, v25, v26
	v_cvt_pk_bf16_f32 v26, v32, v29
	v_cvt_pk_bf16_f32 v27, v30, v27
	global_store_dwordx4 v[88:89], v[24:27], off offset:256
	v_pk_add_f32 v[22:23], v[22:23], v[70:71]
	v_max_f32_e32 v17, 0, v17
	v_mul_f32_e32 v24, v16, v16
	v_max_f32_e32 v16, 0, v21
	v_max_f32_e32 v18, 0, v18
	v_max_f32_e32 v20, 0, v20
	v_mul_f32_e32 v16, v16, v16
	v_mul_f32_e32 v21, v17, v17
	v_max_f32_e32 v17, 0, v22
	v_mul_f32_e32 v22, v18, v18
	v_max_f32_e32 v18, 0, v23
	v_max_f32_e32 v19, 0, v19
	v_pk_add_f32 v[8:9], v[8:9], v[64:65]
	v_mul_f32_e32 v20, v20, v20
	v_mul_f32_e32 v17, v17, v17
	v_mul_f32_e32 v18, v18, v18
	v_mul_f32_e32 v19, v19, v19
	v_cvt_pk_bf16_f32 v16, v20, v16
	v_pk_add_f32 v[12:13], v[12:13], v[68:69]
	v_pk_add_f32 v[10:11], v[10:11], v[66:67]
	v_max_f32_e32 v8, 0, v8
	v_cvt_pk_bf16_f32 v17, v17, v18
	v_cvt_pk_bf16_f32 v18, v24, v21
	v_cvt_pk_bf16_f32 v19, v22, v19
	global_store_dwordx4 v[80:81], v[16:19], off offset:256
	v_pk_add_f32 v[14:15], v[14:15], v[70:71]
	v_max_f32_e32 v9, 0, v9
	v_mul_f32_e32 v16, v8, v8
	v_max_f32_e32 v8, 0, v13
	v_max_f32_e32 v10, 0, v10
	v_max_f32_e32 v12, 0, v12
	v_mul_f32_e32 v8, v8, v8
	v_mul_f32_e32 v13, v9, v9
	v_max_f32_e32 v9, 0, v14
	v_mul_f32_e32 v14, v10, v10
	v_max_f32_e32 v10, 0, v15
	v_max_f32_e32 v11, 0, v11
	v_pk_add_f32 v[2:3], v[2:3], v[66:67]
	v_pk_add_f32 v[0:1], v[0:1], v[64:65]
	v_mul_f32_e32 v12, v12, v12
	v_mul_f32_e32 v9, v9, v9
	v_mul_f32_e32 v10, v10, v10
	v_mul_f32_e32 v11, v11, v11
	v_cvt_pk_bf16_f32 v8, v12, v8
	v_pk_add_f32 v[6:7], v[6:7], v[70:71]
	v_pk_add_f32 v[4:5], v[4:5], v[68:69]
	v_max_f32_e32 v0, 0, v0
	v_max_f32_e32 v1, 0, v1
	v_max_f32_e32 v2, 0, v2
	v_cvt_pk_bf16_f32 v9, v9, v10
	v_cvt_pk_bf16_f32 v10, v16, v13
	v_cvt_pk_bf16_f32 v11, v14, v11
	global_store_dwordx4 v[72:73], v[8:11], off offset:256
	v_max_f32_e32 v3, 0, v3
	v_max_f32_e32 v4, 0, v4
	v_mul_f32_e32 v8, v0, v0
	v_max_f32_e32 v0, 0, v5
	v_mul_f32_e32 v5, v1, v1
	v_max_f32_e32 v1, 0, v6
	v_mul_f32_e32 v6, v2, v2
	v_max_f32_e32 v2, 0, v7
	v_mul_f32_e32 v0, v0, v0
	v_mul_f32_e32 v1, v1, v1
	v_mul_f32_e32 v2, v2, v2
	v_mul_f32_e32 v3, v3, v3
	v_mul_f32_e32 v4, v4, v4
	v_cvt_pk_bf16_f32 v0, v4, v0
	v_cvt_pk_bf16_f32 v1, v1, v2
	v_cvt_pk_bf16_f32 v2, v8, v5
	v_cvt_pk_bf16_f32 v3, v6, v3
	s_nop 1
	global_store_dwordx4 v[74:75], v[0:3], off offset:256
	s_cbranch_vccz .LBB0_288
	s_waitcnt vmcnt(0)
	s_cmpk_gt_u32 s28, 0xff
	s_cbranch_scc1 .LBB0_299
	s_barrier

; #define PG8_STAGE(bufoff, gbase, voff) do { _Pragma("unroll") for (int _i = 0; _i < 2; ++_i) \
;         __builtin_amdgcn_global_load_lds((const unsigned*)((const char*)(gbase) + (voff)[_i]), (PG8_LAS unsigned*)(lds + (bufoff) + ldsw + _i * 8192), 16, 0, 0); } while (0)
; #define PG8_LDA(dst, b, h) do { _Pragma("unroll") for (int m = 0; m < 4; ++m) _Pragma("unroll") for (int k = 0; k < 2; ++k) dst[m][k] = *(const PG8_LAS bf16x8*)(lds + PG8_SA(b, h) + aoff + m * 2048 + k * 1024); } while (0)
; #define PG8_LDB(dst, b, h) do { _Pragma("unroll") for (int n = 0; n < 2; ++n) _Pragma("unroll") for (int k = 0; k < 2; ++k) dst[n][k] = *(const PG8_LAS bf16x8*)(lds + PG8_SB(b, h) + boff + n * 2048 + k * 1024); } while (0)
; #define PG8_MMA(ai, bj, At, Bt) do { __builtin_amdgcn_s_setprio(1); _Pragma("unroll") for (int m = 0; m < 4; ++m) _Pragma("unroll") for (int n = 0; n < 2; ++n) _Pragma("unroll") for (int k = 0; k < 2; ++k) \
;         acc[ai][bj][m][n] = __builtin_amdgcn_mfma_f32_16x16x32_bf16(Bt[n][k], At[m][k], acc[ai][bj][m][n], 0, 0, 0); __builtin_amdgcn_s_setprio(0); } while (0)
; #define PG8_WAIT_L(n) asm volatile("s_waitcnt lgkmcnt(" #n ")" ::: "memory")
; #define PG8_BAR __builtin_amdgcn_s_barrier()
; #define PG8_SCHED __builtin_amdgcn_sched_barrier(0)
; template <class Epi, class Sched>
; __device__ __forceinline__ void gemm_phase(PG8_LAS unsigned char* lds, const Gemm g, const Sched& S, const Epi& E, int tid_in) {
;     ...
;             PG8_LDB(B0, 0, 0); PG8_SCHED; PG8_LDA(At, 0, 0); PG8_STAGE(PG8_SA(1, 1), a1 + hstep, voffA);
;             PG8_WAIT_L(8); PG8_BAR; PG8_WAIT_L(0); PG8_MMA(0, 0, At, B0); PG8_BAR; PG8_SCHED;
;             PG8_LDB(B1, 0, 1); PG8_STAGE(PG8_SB(0, 0), b2, voffB);
;             PG8_BAR; PG8_WAIT_L(0); PG8_MMA(0, 1, At, B1); PG8_BAR;
;             PG8_LDA(At, 0, 1); PG8_STAGE(PG8_SA(0, 0), a2, voffA);
;             PG8_BAR; PG8_WAIT_L(0); PG8_MMA(1, 0, At, B0); PG8_BAR; PG8_SCHED;
.LBB0_325:
	s_add_u32 s16, s14, 0x100
	s_addc_u32 s17, s15, 0
	s_add_i32 s46, 0, 0x10000
	v_add_u32_e32 v138, s46, v141
	ds_read_b128 v[128:131], v138
	ds_read_b128 v[144:147], v138 offset:1024
	ds_read_b128 v[148:151], v138 offset:2048
	ds_read_b128 v[152:155], v138 offset:3072
	s_cmp_eq_u32 s45, 12
	s_cselect_b32 s21, s7, s17
	s_cselect_b32 s20, s41, s16
	s_cselect_b32 s19, s5, s44
	s_cselect_b32 s18, s42, s43
	v_lshl_add_u64 v[138:139], s[14:15], 0, v[134:135]
	s_add_i32 m0, s13, 0xc000
	ds_read_b128 v[156:159], v143
	ds_read_b128 v[160:163], v143 offset:1024
	ds_read_b128 v[164:167], v143 offset:2048
	ds_read_b128 v[168:171], v143 offset:3072
	ds_read_b128 v[172:175], v143 offset:4096
	ds_read_b128 v[176:179], v143 offset:5120
	ds_read_b128 v[180:183], v143 offset:6144
	ds_read_b128 v[184:187], v143 offset:7168
	global_load_lds_dwordx4 v[138:139], off
	v_lshl_add_u64 v[138:139], s[14:15], 0, v[136:137]
	s_add_i32 m0, s13, 0xe000
	s_nop 0
	global_load_lds_dwordx4 v[138:139], off
	s_waitcnt lgkmcnt(8)
	s_barrier
	s_waitcnt lgkmcnt(0)
	s_setprio 1
	s_waitcnt lgkmcnt(0)
	v_mfma_f32_16x16x32_bf16 v[124:127], v[128:131], v[156:159], v[124:127]
	v_mfma_f32_16x16x32_bf16 v[92:95], v[148:151], v[156:159], v[92:95]
	v_mfma_f32_16x16x32_bf16 v[120:123], v[128:131], v[164:167], v[120:123]
	v_mfma_f32_16x16x32_bf16 v[88:91], v[148:151], v[164:167], v[88:91]
	v_mfma_f32_16x16x32_bf16 v[116:119], v[128:131], v[172:175], v[116:119]
	v_mfma_f32_16x16x32_bf16 v[84:87], v[148:151], v[172:175], v[84:87]
	v_mfma_f32_16x16x32_bf16 v[112:115], v[128:131], v[180:183], v[112:115]
	v_mfma_f32_16x16x32_bf16 v[80:83], v[148:151], v[180:183], v[80:83]
	v_mfma_f32_16x16x32_bf16 v[124:127], v[144:147], v[160:163], v[124:127]
	v_mfma_f32_16x16x32_bf16 v[92:95], v[152:155], v[160:163], v[92:95]
	v_mfma_f32_16x16x32_bf16 v[120:123], v[144:147], v[168:171], v[120:123]
	v_mfma_f32_16x16x32_bf16 v[88:91], v[152:155], v[168:171], v[88:91]
	v_mfma_f32_16x16x32_bf16 v[116:119], v[144:147], v[176:179], v[116:119]
	v_mfma_f32_16x16x32_bf16 v[84:87], v[152:155], v[176:179], v[84:87]
	v_mfma_f32_16x16x32_bf16 v[112:115], v[144:147], v[184:187], v[112:115]
	v_mfma_f32_16x16x32_bf16 v[80:83], v[152:155], v[184:187], v[80:83]
	s_setprio 0
	s_barrier
	s_add_i32 s48, 0, 0x14000
	v_add_u32_e32 v138, s48, v141
	s_add_i32 s14, s46, s28
	ds_read_b128 v[188:191], v138
	ds_read_b128 v[194:197], v138 offset:1024
	ds_read_b128 v[200:203], v138 offset:2048
	ds_read_b128 v[204:207], v138 offset:3072
	v_lshl_add_u64 v[138:139], s[18:19], 0, v[192:193]
	s_mov_b32 m0, s14
	v_lshl_add_u64 v[208:209], s[18:19], 0, v[132:133]
	global_load_lds_dwordx4 v[138:139], off
	s_add_i32 m0, s14, 0x2000
	s_nop 0
	global_load_lds_dwordx4 v[208:209], off
	s_barrier
	s_waitcnt lgkmcnt(0)
	s_setprio 1
	s_waitcnt lgkmcnt(0)
	v_mfma_f32_16x16x32_bf16 v[60:63], v[188:191], v[156:159], v[60:63]
	v_mfma_f32_16x16x32_bf16 v[28:31], v[200:203], v[156:159], v[28:31]
	v_mfma_f32_16x16x32_bf16 v[56:59], v[188:191], v[164:167], v[56:59]
	v_mfma_f32_16x16x32_bf16 v[24:27], v[200:203], v[164:167], v[24:27]
	v_mfma_f32_16x16x32_bf16 v[52:55], v[188:191], v[172:175], v[52:55]
	v_mfma_f32_16x16x32_bf16 v[20:23], v[200:203], v[172:175], v[20:23]
	v_mfma_f32_16x16x32_bf16 v[48:51], v[188:191], v[180:183], v[48:51]
	v_mfma_f32_16x16x32_bf16 v[16:19], v[200:203], v[180:183], v[16:19]
	v_mfma_f32_16x16x32_bf16 v[60:63], v[194:197], v[160:163], v[60:63]
	v_mfma_f32_16x16x32_bf16 v[28:31], v[204:207], v[160:163], v[28:31]
	v_mfma_f32_16x16x32_bf16 v[56:59], v[194:197], v[168:171], v[56:59]
	v_mfma_f32_16x16x32_bf16 v[24:27], v[204:207], v[168:171], v[24:27]
	v_mfma_f32_16x16x32_bf16 v[52:55], v[194:197], v[176:179], v[52:55]
	v_mfma_f32_16x16x32_bf16 v[20:23], v[204:207], v[176:179], v[20:23]
	v_mfma_f32_16x16x32_bf16 v[48:51], v[194:197], v[184:187], v[48:51]
	v_mfma_f32_16x16x32_bf16 v[16:19], v[204:207], v[184:187], v[16:19]
	s_setprio 0
	s_mov_b32 m0, s13
	v_lshl_add_u64 v[210:211], s[20:21], 0, v[192:193]
	s_barrier
	ds_read_b128 v[156:159], v143 offset:16384
	ds_read_b128 v[160:163], v143 offset:17408
	ds_read_b128 v[164:167], v143 offset:18432
	ds_read_b128 v[168:171], v143 offset:19456
	ds_read_b128 v[172:175], v143 offset:20480
	ds_read_b128 v[176:179], v143 offset:21504
	ds_read_b128 v[180:183], v143 offset:22528
	ds_read_b128 v[184:187], v143 offset:23552
	global_load_lds_dwordx4 v[210:211], off
	v_lshl_add_u64 v[212:213], s[20:21], 0, v[132:133]
	s_mov_b32 m0, s29
	s_nop 0
	global_load_lds_dwordx4 v[212:213], off
	s_barrier
	s_waitcnt lgkmcnt(0)
	s_setprio 1
	s_waitcnt lgkmcnt(0)
	v_mfma_f32_16x16x32_bf16 v[108:111], v[128:131], v[156:159], v[108:111]
	v_mfma_f32_16x16x32_bf16 v[76:79], v[148:151], v[156:159], v[76:79]
	v_mfma_f32_16x16x32_bf16 v[104:107], v[128:131], v[164:167], v[104:107]
	v_mfma_f32_16x16x32_bf16 v[72:75], v[148:151], v[164:167], v[72:75]
	v_mfma_f32_16x16x32_bf16 v[100:103], v[128:131], v[172:175], v[100:103]
	v_mfma_f32_16x16x32_bf16 v[68:71], v[148:151], v[172:175], v[68:71]
	v_mfma_f32_16x16x32_bf16 v[96:99], v[128:131], v[180:183], v[96:99]
	v_mfma_f32_16x16x32_bf16 v[64:67], v[148:151], v[180:183], v[64:67]
	v_mfma_f32_16x16x32_bf16 v[108:111], v[144:147], v[160:163], v[108:111]
	v_mfma_f32_16x16x32_bf16 v[76:79], v[152:155], v[160:163], v[76:79]
	v_mfma_f32_16x16x32_bf16 v[104:107], v[144:147], v[168:171], v[104:107]
	v_mfma_f32_16x16x32_bf16 v[72:75], v[152:155], v[168:171], v[72:75]
	v_mfma_f32_16x16x32_bf16 v[100:103], v[144:147], v[176:179], v[100:103]
	v_mfma_f32_16x16x32_bf16 v[68:71], v[152:155], v[176:179], v[68:71]
	v_mfma_f32_16x16x32_bf16 v[96:99], v[144:147], v[184:187], v[96:99]
	v_mfma_f32_16x16x32_bf16 v[64:67], v[152:155], v[184:187], v[64:67]
	s_setprio 0
	s_barrier
; #define PG8_STAGE(bufoff, gbase, voff) do { _Pragma("unroll") for (int _i = 0; _i < 2; ++_i) \
;         __builtin_amdgcn_global_load_lds((const unsigned*)((const char*)(gbase) + (voff)[_i]), (PG8_LAS unsigned*)(lds + (bufoff) + ldsw + _i * 8192), 16, 0, 0); } while (0)
; #define PG8_LDA(dst, b, h) do { _Pragma("unroll") for (int m = 0; m < 4; ++m) _Pragma("unroll") for (int k = 0; k < 2; ++k) dst[m][k] = *(const PG8_LAS bf16x8*)(lds + PG8_SA(b, h) + aoff + m * 2048 + k * 1024); } while (0)
; #define PG8_LDB(dst, b, h) do { _Pragma("unroll") for (int n = 0; n < 2; ++n) _Pragma("unroll") for (int k = 0; k < 2; ++k) dst[n][k] = *(const PG8_LAS bf16x8*)(lds + PG8_SB(b, h) + boff + n * 2048 + k * 1024); } while (0)
; #define PG8_MMA(ai, bj, At, Bt) do { __builtin_amdgcn_s_setprio(1); _Pragma("unroll") for (int m = 0; m < 4; ++m) _Pragma("unroll") for (int n = 0; n < 2; ++n) _Pragma("unroll") for (int k = 0; k < 2; ++k) \
;         acc[ai][bj][m][n] = __builtin_amdgcn_mfma_f32_16x16x32_bf16(Bt[n][k], At[m][k], acc[ai][bj][m][n], 0, 0, 0); __builtin_amdgcn_s_setprio(0); } while (0)
; #define PG8_WAIT_V(n) asm volatile("s_waitcnt vmcnt(" #n ")" ::: "memory")
; #define PG8_WAIT_L(n) asm volatile("s_waitcnt lgkmcnt(" #n ")" ::: "memory")
; #define PG8_BAR __builtin_amdgcn_s_barrier()
; #define PG8_SCHED __builtin_amdgcn_sched_barrier(0)
; template <class Epi, class Sched>
; __device__ __forceinline__ void gemm_phase(PG8_LAS unsigned char* lds, const Gemm g, const Sched& S, const Epi& E, int tid_in) {
;     ...
;             PG8_STAGE(PG8_SB(0, 1), b2 + hstep, voffB);
;             PG8_WAIT_V(6); PG8_BAR; PG8_MMA(1, 1, At, B1); PG8_BAR;
;             PG8_LDB(B0, 1, 0); PG8_SCHED; PG8_LDA(At, 1, 0); PG8_STAGE(PG8_SA(0, 1), a2 + hstep, voffA);
;             PG8_WAIT_L(8); PG8_BAR; PG8_WAIT_L(0); PG8_MMA(0, 0, At, B0); PG8_BAR; PG8_SCHED;
;             PG8_LDB(B1, 1, 1); PG8_STAGE(PG8_SB(1, 0), b3, voffB);
;             PG8_BAR; PG8_WAIT_L(0); PG8_MMA(0, 1, At, B1); PG8_BAR;
;             PG8_LDA(At, 1, 1); PG8_STAGE(PG8_SA(1, 0), a3, voffA);
	s_add_u32 s14, s18, 0x40000
	s_addc_u32 s15, s19, 0
	s_add_i32 s46, s48, s28
	v_lshl_add_u64 v[128:129], s[14:15], 0, v[192:193]
	s_mov_b32 m0, s46
	s_nop 0
	global_load_lds_dwordx4 v[128:129], off
	v_lshl_add_u64 v[128:129], s[14:15], 0, v[132:133]
	s_add_i32 m0, s46, 0x2000
	s_nop 0
	global_load_lds_dwordx4 v[128:129], off
	s_waitcnt vmcnt(6)
	s_barrier
	s_setprio 1
	v_mfma_f32_16x16x32_bf16 v[44:47], v[188:191], v[156:159], v[44:47]
	v_mfma_f32_16x16x32_bf16 v[12:15], v[200:203], v[156:159], v[12:15]
	v_mfma_f32_16x16x32_bf16 v[40:43], v[188:191], v[164:167], v[40:43]
	v_mfma_f32_16x16x32_bf16 v[8:11], v[200:203], v[164:167], v[8:11]
	v_mfma_f32_16x16x32_bf16 v[36:39], v[188:191], v[172:175], v[36:39]
	v_mfma_f32_16x16x32_bf16 v[4:7], v[200:203], v[172:175], v[4:7]
	v_mfma_f32_16x16x32_bf16 v[32:35], v[188:191], v[180:183], v[32:35]
	v_mfma_f32_16x16x32_bf16 v[0:3], v[200:203], v[180:183], v[0:3]
	v_mfma_f32_16x16x32_bf16 v[44:47], v[194:197], v[160:163], v[44:47]
	v_mfma_f32_16x16x32_bf16 v[12:15], v[204:207], v[160:163], v[12:15]
	v_mfma_f32_16x16x32_bf16 v[40:43], v[194:197], v[168:171], v[40:43]
	v_mfma_f32_16x16x32_bf16 v[8:11], v[204:207], v[168:171], v[8:11]
	v_mfma_f32_16x16x32_bf16 v[36:39], v[194:197], v[176:179], v[36:39]
	v_mfma_f32_16x16x32_bf16 v[4:7], v[204:207], v[176:179], v[4:7]
	v_mfma_f32_16x16x32_bf16 v[32:35], v[194:197], v[184:187], v[32:35]
	v_mfma_f32_16x16x32_bf16 v[0:3], v[204:207], v[184:187], v[0:3]
	s_setprio 0
	s_add_i32 s46, 0, 0x18000
	v_add_u32_e32 v152, s46, v141
	s_barrier
	ds_read_b128 v[128:131], v152
	ds_read_b128 v[144:147], v152 offset:1024
	ds_read_b128 v[148:151], v152 offset:2048
	ds_read_b128 v[152:155], v152 offset:3072
	s_add_u32 s14, s20, 0x40000
	s_addc_u32 s15, s21, 0
	s_mov_b32 m0, s30
	v_lshl_add_u64 v[188:189], s[14:15], 0, v[192:193]
	ds_read_b128 v[156:159], v143 offset:32768
	ds_read_b128 v[160:163], v143 offset:33792
	ds_read_b128 v[164:167], v143 offset:34816
	ds_read_b128 v[168:171], v143 offset:35840
	ds_read_b128 v[172:175], v143 offset:36864
	ds_read_b128 v[176:179], v143 offset:37888
	ds_read_b128 v[180:183], v143 offset:38912
	ds_read_b128 v[184:187], v143 offset:39936
	global_load_lds_dwordx4 v[188:189], off
	v_lshl_add_u64 v[188:189], s[14:15], 0, v[132:133]
	s_mov_b32 m0, s31
	s_nop 0
	global_load_lds_dwordx4 v[188:189], off
	s_waitcnt lgkmcnt(8)
	s_barrier
	s_waitcnt lgkmcnt(0)
	s_setprio 1
	s_waitcnt lgkmcnt(0)
	v_mfma_f32_16x16x32_bf16 v[124:127], v[128:131], v[156:159], v[124:127]
	v_mfma_f32_16x16x32_bf16 v[92:95], v[148:151], v[156:159], v[92:95]
	v_mfma_f32_16x16x32_bf16 v[120:123], v[128:131], v[164:167], v[120:123]
	v_mfma_f32_16x16x32_bf16 v[88:91], v[148:151], v[164:167], v[88:91]
	v_mfma_f32_16x16x32_bf16 v[116:119], v[128:131], v[172:175], v[116:119]
	v_mfma_f32_16x16x32_bf16 v[84:87], v[148:151], v[172:175], v[84:87]
	v_mfma_f32_16x16x32_bf16 v[112:115], v[128:131], v[180:183], v[112:115]
	v_mfma_f32_16x16x32_bf16 v[80:83], v[148:151], v[180:183], v[80:83]
	v_mfma_f32_16x16x32_bf16 v[124:127], v[144:147], v[160:163], v[124:127]
	v_mfma_f32_16x16x32_bf16 v[92:95], v[152:155], v[160:163], v[92:95]
	v_mfma_f32_16x16x32_bf16 v[120:123], v[144:147], v[168:171], v[120:123]
	v_mfma_f32_16x16x32_bf16 v[88:91], v[152:155], v[168:171], v[88:91]
	v_mfma_f32_16x16x32_bf16 v[116:119], v[144:147], v[176:179], v[116:119]
	v_mfma_f32_16x16x32_bf16 v[84:87], v[152:155], v[176:179], v[84:87]
	v_mfma_f32_16x16x32_bf16 v[112:115], v[144:147], v[184:187], v[112:115]
	v_mfma_f32_16x16x32_bf16 v[80:83], v[152:155], v[184:187], v[80:83]
	s_setprio 0
	s_barrier
	s_add_i32 s20, 0, 0x1c000
	s_add_i32 s14, s46, s28
	v_add_u32_e32 v199, s20, v141
	v_lshl_add_u64 v[138:139], v[138:139], 0, s[74:75]
	s_mov_b32 m0, s14
	ds_read_b128 v[188:191], v199
	ds_read_b128 v[194:197], v199 offset:1024
	ds_read_b128 v[200:203], v199 offset:2048
	ds_read_b128 v[204:207], v199 offset:3072
	global_load_lds_dwordx4 v[138:139], off
	v_lshl_add_u64 v[138:139], v[208:209], 0, s[74:75]
	s_add_i32 m0, s14, 0x2000
	s_nop 0
	global_load_lds_dwordx4 v[138:139], off
	s_barrier
	s_waitcnt lgkmcnt(0)
	s_setprio 1
	s_waitcnt lgkmcnt(0)
	v_mfma_f32_16x16x32_bf16 v[60:63], v[188:191], v[156:159], v[60:63]
	v_mfma_f32_16x16x32_bf16 v[28:31], v[200:203], v[156:159], v[28:31]
	v_mfma_f32_16x16x32_bf16 v[56:59], v[188:191], v[164:167], v[56:59]
	v_mfma_f32_16x16x32_bf16 v[24:27], v[200:203], v[164:167], v[24:27]
	v_mfma_f32_16x16x32_bf16 v[52:55], v[188:191], v[172:175], v[52:55]
	v_mfma_f32_16x16x32_bf16 v[20:23], v[200:203], v[172:175], v[20:23]
	v_mfma_f32_16x16x32_bf16 v[48:51], v[188:191], v[180:183], v[48:51]
	v_mfma_f32_16x16x32_bf16 v[16:19], v[200:203], v[180:183], v[16:19]
	v_mfma_f32_16x16x32_bf16 v[60:63], v[194:197], v[160:163], v[60:63]
	v_mfma_f32_16x16x32_bf16 v[28:31], v[204:207], v[160:163], v[28:31]
	v_mfma_f32_16x16x32_bf16 v[56:59], v[194:197], v[168:171], v[56:59]
	v_mfma_f32_16x16x32_bf16 v[24:27], v[204:207], v[168:171], v[24:27]
	v_mfma_f32_16x16x32_bf16 v[52:55], v[194:197], v[176:179], v[52:55]
	v_mfma_f32_16x16x32_bf16 v[20:23], v[204:207], v[176:179], v[20:23]
	v_mfma_f32_16x16x32_bf16 v[48:51], v[194:197], v[184:187], v[48:51]
	v_mfma_f32_16x16x32_bf16 v[16:19], v[204:207], v[184:187], v[16:19]
	s_setprio 0
	s_mov_b32 m0, s38
	v_lshl_add_u64 v[138:139], v[210:211], 0, s[74:75]
	s_barrier
	ds_read_b128 v[156:159], v143 offset:49152
	ds_read_b128 v[160:163], v143 offset:50176
	ds_read_b128 v[164:167], v143 offset:51200
	ds_read_b128 v[168:171], v143 offset:52224
	ds_read_b128 v[172:175], v143 offset:53248
	ds_read_b128 v[176:179], v143 offset:54272
	ds_read_b128 v[180:183], v143 offset:55296
	ds_read_b128 v[184:187], v143 offset:56320
	global_load_lds_dwordx4 v[138:139], off
	v_lshl_add_u64 v[138:139], v[212:213], 0, s[74:75]
	s_mov_b32 m0, s39
	s_nop 0
	global_load_lds_dwordx4 v[138:139], off
	s_barrier
; #define PG8_STAGE(bufoff, gbase, voff) do { _Pragma("unroll") for (int _i = 0; _i < 2; ++_i) \
;         __builtin_amdgcn_global_load_lds((const unsigned*)((const char*)(gbase) + (voff)[_i]), (PG8_LAS unsigned*)(lds + (bufoff) + ldsw + _i * 8192), 16, 0, 0); } while (0)
; #define PG8_MMA(ai, bj, At, Bt) do { __builtin_amdgcn_s_setprio(1); _Pragma("unroll") for (int m = 0; m < 4; ++m) _Pragma("unroll") for (int n = 0; n < 2; ++n) _Pragma("unroll") for (int k = 0; k < 2; ++k) \
;         acc[ai][bj][m][n] = __builtin_amdgcn_mfma_f32_16x16x32_bf16(Bt[n][k], At[m][k], acc[ai][bj][m][n], 0, 0, 0); __builtin_amdgcn_s_setprio(0); } while (0)
; #define PG8_WAIT_V(n) asm volatile("s_waitcnt vmcnt(" #n ")" ::: "memory")
; #define PG8_WAIT_L(n) asm volatile("s_waitcnt lgkmcnt(" #n ")" ::: "memory")
; #define PG8_BAR __builtin_amdgcn_s_barrier()
; #define PG8_SCHED __builtin_amdgcn_sched_barrier(0)
; template <class Epi, class Sched>
; __device__ __forceinline__ void gemm_phase(PG8_LAS unsigned char* lds, const Gemm g, const Sched& S, const Epi& E, int tid_in) {
;     ...
;             PG8_BAR; PG8_WAIT_L(0); PG8_MMA(1, 0, At, B0); PG8_BAR; PG8_SCHED;
;             PG8_STAGE(PG8_SB(1, 1), b3 + hstep, voffB);
;             PG8_WAIT_V(6); PG8_BAR; PG8_MMA(1, 1, At, B1); PG8_BAR;
;     __device__ __forceinline__ void operator()(f32x4 (&acc)[2][2][4][2], const Unit& u, int wr, int wc, int fr, int fq) const {
;         const int row0 = u.pm * 256 + wr * 64 + fr, col0 = u.pn * 256 + wc * 32 + 4 * fq;
;         const float* gr = gate + (size_t)(bbase + (u.pm * 256) / SEQ) * MODW;
; #pragma unroll
;         for (int bj = 0; bj < 2; ++bj)
; #pragma unroll
;             for (int n = 0; n < 2; ++n) { const int col = col0 + bj * 128 + n * 16; const f32x4 gv = *(const f32x4*)(gr + col);
;                 f32x4 bv = (f32x4){0.f, 0.f, 0.f, 0.f}; if (bias) bv = *(const f32x4*)(bias + col);
	s_waitcnt lgkmcnt(0)
	s_setprio 1
	s_waitcnt lgkmcnt(0)
	v_mfma_f32_16x16x32_bf16 v[108:111], v[128:131], v[156:159], v[108:111]
	v_mfma_f32_16x16x32_bf16 v[76:79], v[148:151], v[156:159], v[76:79]
	v_mfma_f32_16x16x32_bf16 v[104:107], v[128:131], v[164:167], v[104:107]
	v_mfma_f32_16x16x32_bf16 v[72:75], v[148:151], v[164:167], v[72:75]
	v_mfma_f32_16x16x32_bf16 v[100:103], v[128:131], v[172:175], v[100:103]
	v_mfma_f32_16x16x32_bf16 v[68:71], v[148:151], v[172:175], v[68:71]
	v_mfma_f32_16x16x32_bf16 v[96:99], v[128:131], v[180:183], v[96:99]
	v_mfma_f32_16x16x32_bf16 v[64:67], v[148:151], v[180:183], v[64:67]
	v_mfma_f32_16x16x32_bf16 v[108:111], v[144:147], v[160:163], v[108:111]
	v_mfma_f32_16x16x32_bf16 v[76:79], v[152:155], v[160:163], v[76:79]
	v_mfma_f32_16x16x32_bf16 v[104:107], v[144:147], v[168:171], v[104:107]
	v_mfma_f32_16x16x32_bf16 v[72:75], v[152:155], v[168:171], v[72:75]
	v_mfma_f32_16x16x32_bf16 v[100:103], v[144:147], v[176:179], v[100:103]
	v_mfma_f32_16x16x32_bf16 v[68:71], v[152:155], v[176:179], v[68:71]
	v_mfma_f32_16x16x32_bf16 v[96:99], v[144:147], v[184:187], v[96:99]
	v_mfma_f32_16x16x32_bf16 v[64:67], v[152:155], v[184:187], v[64:67]
	s_setprio 0
	s_barrier
	s_add_u32 s14, s18, 0x40080
	s_addc_u32 s15, s19, 0
	s_add_i32 s18, s20, s28
	v_lshl_add_u64 v[128:129], s[14:15], 0, v[192:193]
	s_mov_b32 m0, s18
	s_nop 0
	global_load_lds_dwordx4 v[128:129], off
	v_lshl_add_u64 v[128:129], s[14:15], 0, v[132:133]
	s_add_i32 m0, s18, 0x2000
	s_nop 0
	global_load_lds_dwordx4 v[128:129], off
	s_waitcnt vmcnt(6)
	s_barrier
	s_setprio 1
	v_mfma_f32_16x16x32_bf16 v[44:47], v[188:191], v[156:159], v[44:47]
	v_mfma_f32_16x16x32_bf16 v[12:15], v[200:203], v[156:159], v[12:15]
	v_mfma_f32_16x16x32_bf16 v[40:43], v[188:191], v[164:167], v[40:43]
	v_mfma_f32_16x16x32_bf16 v[8:11], v[200:203], v[164:167], v[8:11]
	v_mfma_f32_16x16x32_bf16 v[36:39], v[188:191], v[172:175], v[36:39]
	v_mfma_f32_16x16x32_bf16 v[4:7], v[200:203], v[172:175], v[4:7]
	v_mfma_f32_16x16x32_bf16 v[32:35], v[188:191], v[180:183], v[32:35]
	v_mfma_f32_16x16x32_bf16 v[0:3], v[200:203], v[180:183], v[0:3]
	v_mfma_f32_16x16x32_bf16 v[44:47], v[194:197], v[160:163], v[44:47]
	v_mfma_f32_16x16x32_bf16 v[12:15], v[204:207], v[160:163], v[12:15]
	v_mfma_f32_16x16x32_bf16 v[40:43], v[194:197], v[168:171], v[40:43]
	v_mfma_f32_16x16x32_bf16 v[8:11], v[204:207], v[168:171], v[8:11]
	v_mfma_f32_16x16x32_bf16 v[36:39], v[194:197], v[176:179], v[36:39]
	v_mfma_f32_16x16x32_bf16 v[4:7], v[204:207], v[176:179], v[4:7]
	v_mfma_f32_16x16x32_bf16 v[32:35], v[194:197], v[184:187], v[32:35]
	v_mfma_f32_16x16x32_bf16 v[0:3], v[204:207], v[184:187], v[0:3]
	s_setprio 0
	s_add_i32 s45, s45, 2
	s_add_u32 s43, s43, 0x100
	s_addc_u32 s44, s44, 0
	s_cmp_gt_u32 s45, 13
	s_mov_b64 s[14:15], s[16:17]
	s_barrier
	s_cbranch_scc0 .LBB0_325
	s_ashr_i32 s5, s12, 31
	s_lshr_b32 s5, s5, 29
	s_add_i32 s5, s12, s5
	s_ashr_i32 s5, s5, 3
	s_add_i32 s5, s5, s76
	s_mul_hi_i32 s7, s5, 0x6000
	s_mulk_i32 s5, 0x6000
	v_lshl_or_b32 v146, s33, 8, v142
	s_add_u32 s14, s36, s5
	s_addc_u32 s15, s37, s7
	v_ashrrev_i32_e32 v147, 31, v146
	v_lshl_add_u64 v[138:139], v[146:147], 2, s[14:15]
	global_load_dwordx4 v[128:131], v[138:139], off
	global_load_dwordx4 v[152:155], v[138:139], off offset:64
	global_load_dwordx4 v[156:159], v[138:139], off offset:512
	global_load_dwordx4 v[160:163], v[138:139], off offset:576
	v_lshl_add_u32 v144, s12, 8, v140
	v_pk_add_f32 v[124:125], v[124:125], 0 op_sel_hi:[1,0]
	v_ashrrev_i32_e32 v145, 31, v144
	v_pk_add_f32 v[126:127], v[126:127], 0 op_sel_hi:[1,0]
	v_pk_add_f32 v[120:121], v[120:121], 0 op_sel_hi:[1,0]
	v_pk_add_f32 v[122:123], v[122:123], 0 op_sel_hi:[1,0]
	v_pk_add_f32 v[116:117], v[116:117], 0 op_sel_hi:[1,0]
	v_pk_add_f32 v[118:119], v[118:119], 0 op_sel_hi:[1,0]
	v_pk_add_f32 v[112:113], v[112:113], 0 op_sel_hi:[1,0]
	v_pk_add_f32 v[114:115], v[114:115], 0 op_sel_hi:[1,0]
	v_pk_add_f32 v[110:111], v[110:111], 0 op_sel_hi:[1,0]
	v_pk_add_f32 v[108:109], v[108:109], 0 op_sel_hi:[1,0]
	v_pk_add_f32 v[106:107], v[106:107], 0 op_sel_hi:[1,0]
	v_pk_add_f32 v[104:105], v[104:105], 0 op_sel_hi:[1,0]
	v_pk_add_f32 v[102:103], v[102:103], 0 op_sel_hi:[1,0]
	v_pk_add_f32 v[100:101], v[100:101], 0 op_sel_hi:[1,0]
	v_pk_add_f32 v[98:99], v[98:99], 0 op_sel_hi:[1,0]
	v_pk_add_f32 v[96:97], v[96:97], 0 op_sel_hi:[1,0]
	s_mov_b32 s5, 0x58000
	s_mov_b64 s[14:15], 0x40000
	v_pk_add_f32 v[92:93], v[92:93], 0 op_sel_hi:[1,0]
	v_pk_add_f32 v[88:89], v[88:89], 0 op_sel_hi:[1,0]
	v_pk_add_f32 v[84:85], v[84:85], 0 op_sel_hi:[1,0]
	v_pk_add_f32 v[80:81], v[80:81], 0 op_sel_hi:[1,0]
	v_pk_add_f32 v[76:77], v[76:77], 0 op_sel_hi:[1,0]
	v_pk_add_f32 v[72:73], v[72:73], 0 op_sel_hi:[1,0]
	v_pk_add_f32 v[68:69], v[68:69], 0 op_sel_hi:[1,0]
	v_pk_add_f32 v[64:65], v[64:65], 0 op_sel_hi:[1,0]
	v_pk_add_f32 v[94:95], v[94:95], 0 op_sel_hi:[1,0]
	v_pk_add_f32 v[90:91], v[90:91], 0 op_sel_hi:[1,0]
	v_pk_add_f32 v[86:87], v[86:87], 0 op_sel_hi:[1,0]
	v_pk_add_f32 v[82:83], v[82:83], 0 op_sel_hi:[1,0]
	v_pk_add_f32 v[78:79], v[78:79], 0 op_sel_hi:[1,0]
	v_pk_add_f32 v[74:75], v[74:75], 0 op_sel_hi:[1,0]
	v_pk_add_f32 v[70:71], v[70:71], 0 op_sel_hi:[1,0]
	v_pk_add_f32 v[66:67], v[66:67], 0 op_sel_hi:[1,0]
	v_pk_add_f32 v[60:61], v[60:61], 0 op_sel_hi:[1,0]
	v_pk_add_f32 v[56:57], v[56:57], 0 op_sel_hi:[1,0]
	v_pk_add_f32 v[52:53], v[52:53], 0 op_sel_hi:[1,0]
	v_pk_add_f32 v[48:49], v[48:49], 0 op_sel_hi:[1,0]
	v_pk_add_f32 v[44:45], v[44:45], 0 op_sel_hi:[1,0]
	v_pk_add_f32 v[40:41], v[40:41], 0 op_sel_hi:[1,0]
	v_pk_add_f32 v[36:37], v[36:37], 0 op_sel_hi:[1,0]
	v_pk_add_f32 v[32:33], v[32:33], 0 op_sel_hi:[1,0]
	v_pk_add_f32 v[62:63], v[62:63], 0 op_sel_hi:[1,0]
	v_pk_add_f32 v[58:59], v[58:59], 0 op_sel_hi:[1,0]
	v_pk_add_f32 v[54:55], v[54:55], 0 op_sel_hi:[1,0]
	v_pk_add_f32 v[50:51], v[50:51], 0 op_sel_hi:[1,0]
	v_pk_add_f32 v[46:47], v[46:47], 0 op_sel_hi:[1,0]
	v_pk_add_f32 v[42:43], v[42:43], 0 op_sel_hi:[1,0]
	v_pk_add_f32 v[38:39], v[38:39], 0 op_sel_hi:[1,0]
	v_pk_add_f32 v[34:35], v[34:35], 0 op_sel_hi:[1,0]
	v_pk_add_f32 v[28:29], v[28:29], 0 op_sel_hi:[1,0]
	v_pk_add_f32 v[24:25], v[24:25], 0 op_sel_hi:[1,0]
	v_pk_add_f32 v[20:21], v[20:21], 0 op_sel_hi:[1,0]
	v_pk_add_f32 v[16:17], v[16:17], 0 op_sel_hi:[1,0]
	v_pk_add_f32 v[12:13], v[12:13], 0 op_sel_hi:[1,0]
	v_pk_add_f32 v[8:9], v[8:9], 0 op_sel_hi:[1,0]
	v_pk_add_f32 v[4:5], v[4:5], 0 op_sel_hi:[1,0]
	v_pk_add_f32 v[0:1], v[0:1], 0 op_sel_hi:[1,0]
	v_pk_add_f32 v[30:31], v[30:31], 0 op_sel_hi:[1,0]
	v_pk_add_f32 v[26:27], v[26:27], 0 op_sel_hi:[1,0]
	v_pk_add_f32 v[22:23], v[22:23], 0 op_sel_hi:[1,0]
	v_pk_add_f32 v[18:19], v[18:19], 0 op_sel_hi:[1,0]
	v_pk_add_f32 v[14:15], v[14:15], 0 op_sel_hi:[1,0]
	v_pk_add_f32 v[10:11], v[10:11], 0 op_sel_hi:[1,0]
	v_pk_add_f32 v[6:7], v[6:7], 0 op_sel_hi:[1,0]
	v_pk_add_f32 v[2:3], v[2:3], 0 op_sel_hi:[1,0]
	s_mov_b32 s33, s4
	s_mov_b32 s12, s6
	s_mov_b64 s[16:17], s[10:11]
	s_waitcnt vmcnt(0)
; __device__ __forceinline__ unsigned cvt_pk_bf16(float lo, float hi) { unsigned r; asm volatile("s_nop 0\n\tv_cvt_pk_bf16_f32 %0, %1, %2\n\ts_nop 1" : "=v"(r) : "v"(lo), "v"(hi)); return r; }
;     __device__ __forceinline__ void operator()(f32x4 (&acc)[2][2][4][2], const Unit& u, int wr, int wc, int fr, int fq) const {
;     ...
;         for (int bj = 0; bj < 2; ++bj)
; #pragma unroll
;             for (int n = 0; n < 2; ++n) { const int col = col0 + bj * 128 + n * 16; const f32x4 gv = *(const f32x4*)(gr + col);
;                 f32x4 bv = (f32x4){0.f, 0.f, 0.f, 0.f}; if (bias) bv = *(const f32x4*)(bias + col);
; #pragma unroll
;                 for (int ai = 0; ai < 2; ++ai)
; #pragma unroll
;                     for (int m = 0; m < 4; ++m) { const size_t row = row0 + ai * 128 + m * 16;
;                         const f32x4 o = gv * (acc[ai][bj][m][n] + bv); u32x2 w; w.x = cvt_pk_bf16(o[0], o[1]); w.y = cvt_pk_bf16(o[2], o[3]);
;                         *(u32x2*)(O + row * 1024 + col) = w; } }
	v_pk_mul_f32 v[124:125], v[124:125], v[128:129]
	v_pk_mul_f32 v[126:127], v[126:127], v[130:131]
	v_cvt_pk_bf16_f32 v148, v124, v125
	v_lshlrev_b64 v[124:125], 11, v[144:145]
	v_cvt_pk_bf16_f32 v149, v126, v127
	v_lshl_add_u64 v[124:125], s[0:1], 0, v[124:125]
	v_lshlrev_b64 v[126:127], 1, v[146:147]
	v_or_b32_e32 v146, 16, v144
	v_lshl_add_u64 v[124:125], v[124:125], 0, v[126:127]
	v_ashrrev_i32_e32 v147, 31, v146
	v_pk_mul_f32 v[120:121], v[120:121], v[128:129]
	global_store_dwordx2 v[124:125], v[148:149], off
	v_pk_mul_f32 v[122:123], v[122:123], v[130:131]
	v_cvt_pk_bf16_f32 v148, v120, v121
	v_lshlrev_b64 v[120:121], 11, v[146:147]
	v_cvt_pk_bf16_f32 v149, v122, v123
	v_lshl_add_u64 v[120:121], s[0:1], 0, v[120:121]
	v_or_b32_e32 v122, 32, v144
	v_lshl_add_u64 v[120:121], v[120:121], 0, v[126:127]
	v_ashrrev_i32_e32 v123, 31, v122
	v_pk_mul_f32 v[116:117], v[116:117], v[128:129]
	global_store_dwordx2 v[120:121], v[148:149], off
	v_pk_mul_f32 v[118:119], v[118:119], v[130:131]
	v_cvt_pk_bf16_f32 v146, v116, v117
	v_lshlrev_b64 v[116:117], 11, v[122:123]
	v_cvt_pk_bf16_f32 v147, v118, v119
	v_lshl_add_u64 v[116:117], s[0:1], 0, v[116:117]
	v_or_b32_e32 v118, 48, v144
	v_lshl_add_u64 v[116:117], v[116:117], 0, v[126:127]
	v_ashrrev_i32_e32 v119, 31, v118
	v_pk_mul_f32 v[112:113], v[112:113], v[128:129]
	global_store_dwordx2 v[116:117], v[146:147], off
	v_cvt_pk_bf16_f32 v122, v112, v113
	v_lshlrev_b64 v[112:113], 11, v[118:119]
	v_lshl_add_u64 v[112:113], s[0:1], 0, v[112:113]
	v_pk_mul_f32 v[114:115], v[114:115], v[130:131]
	v_lshl_add_u64 v[112:113], v[112:113], 0, v[126:127]
	v_pk_mul_f32 v[110:111], v[110:111], v[130:131]
	v_cvt_pk_bf16_f32 v123, v114, v115
	global_store_dwordx2 v[112:113], v[122:123], off
	v_pk_mul_f32 v[108:109], v[108:109], v[128:129]
	v_pk_mul_f32 v[106:107], v[106:107], v[130:131]
	v_cvt_pk_bf16_f32 v114, v108, v109
	v_cvt_pk_bf16_f32 v115, v110, v111
	v_add_co_u32_e32 v110, vcc, s63, v124
	v_pk_mul_f32 v[104:105], v[104:105], v[128:129]
	s_nop 0
	v_addc_co_u32_e32 v111, vcc, 0, v125, vcc
	global_store_dwordx2 v[110:111], v[114:115], off
	v_cvt_pk_bf16_f32 v110, v104, v105
	v_cvt_pk_bf16_f32 v111, v106, v107
	v_add_co_u32_e32 v106, vcc, s66, v124
	v_pk_mul_f32 v[102:103], v[102:103], v[130:131]
	s_nop 0
	v_addc_co_u32_e32 v107, vcc, 0, v125, vcc
	global_store_dwordx2 v[106:107], v[110:111], off
	v_pk_mul_f32 v[100:101], v[100:101], v[128:129]
	v_pk_mul_f32 v[98:99], v[98:99], v[130:131]
	v_cvt_pk_bf16_f32 v106, v100, v101
	v_cvt_pk_bf16_f32 v107, v102, v103
	v_add_co_u32_e32 v102, vcc, s55, v124
	v_pk_mul_f32 v[96:97], v[96:97], v[128:129]
	s_nop 0
	v_addc_co_u32_e32 v103, vcc, 0, v125, vcc
	global_store_dwordx2 v[102:103], v[106:107], off
	v_cvt_pk_bf16_f32 v96, v96, v97
	v_cvt_pk_bf16_f32 v97, v98, v99
	v_add_co_u32_e32 v98, vcc, s5, v124
	v_lshl_add_u64 v[108:109], v[124:125], 0, s[14:15]
	s_nop 0
	v_addc_co_u32_e32 v99, vcc, 0, v125, vcc
	global_store_dwordx2 v[98:99], v[96:97], off
	s_nop 0
	v_mov_b32_e32 v96, v152
	v_mov_b32_e32 v97, v153
	v_mov_b32_e32 v98, v154
	v_mov_b32_e32 v99, v155
	s_mov_b64 s[14:15], 0x50000
	v_lshl_add_u64 v[100:101], v[124:125], 0, s[14:15]
	s_mov_b64 s[14:15], 0x58000
	v_lshl_add_u64 v[104:105], v[124:125], 0, s[64:65]
	v_lshl_add_u64 v[102:103], v[124:125], 0, s[14:15]
	s_and_b64 vcc, exec, s[2:3]
	s_mov_b64 s[14:15], s[8:9]
	v_pk_mul_f32 v[92:93], v[92:93], v[96:97]
	v_pk_mul_f32 v[88:89], v[88:89], v[96:97]
	v_pk_mul_f32 v[84:85], v[84:85], v[96:97]
	v_pk_mul_f32 v[80:81], v[80:81], v[96:97]
	v_pk_mul_f32 v[76:77], v[76:77], v[96:97]
	v_pk_mul_f32 v[72:73], v[72:73], v[96:97]
	v_pk_mul_f32 v[68:69], v[68:69], v[96:97]
	v_pk_mul_f32 v[64:65], v[64:65], v[96:97]
	v_pk_mul_f32 v[94:95], v[94:95], v[98:99]
	v_cvt_pk_bf16_f32 v92, v92, v93
	v_pk_mul_f32 v[90:91], v[90:91], v[98:99]
	v_cvt_pk_bf16_f32 v93, v94, v95
	global_store_dwordx2 v[124:125], v[92:93], off offset:32
	v_cvt_pk_bf16_f32 v88, v88, v89
	v_cvt_pk_bf16_f32 v89, v90, v91
	global_store_dwordx2 v[120:121], v[88:89], off offset:32
	v_pk_mul_f32 v[86:87], v[86:87], v[98:99]
	v_cvt_pk_bf16_f32 v84, v84, v85
	v_pk_mul_f32 v[82:83], v[82:83], v[98:99]
	v_cvt_pk_bf16_f32 v85, v86, v87
	global_store_dwordx2 v[116:117], v[84:85], off offset:32
	v_cvt_pk_bf16_f32 v80, v80, v81
	v_cvt_pk_bf16_f32 v81, v82, v83
	global_store_dwordx2 v[112:113], v[80:81], off offset:32
; __device__ __forceinline__ unsigned cvt_pk_bf16(float lo, float hi) { unsigned r; asm volatile("s_nop 0\n\tv_cvt_pk_bf16_f32 %0, %1, %2\n\ts_nop 1" : "=v"(r) : "v"(lo), "v"(hi)); return r; }
;     __device__ __forceinline__ void operator()(f32x4 (&acc)[2][2][4][2], const Unit& u, int wr, int wc, int fr, int fq) const {
;     ...
;         for (int bj = 0; bj < 2; ++bj)
; #pragma unroll
;             for (int n = 0; n < 2; ++n) { const int col = col0 + bj * 128 + n * 16; const f32x4 gv = *(const f32x4*)(gr + col);
;                 f32x4 bv = (f32x4){0.f, 0.f, 0.f, 0.f}; if (bias) bv = *(const f32x4*)(bias + col);
; #pragma unroll
;                 for (int ai = 0; ai < 2; ++ai)
; #pragma unroll
;                     for (int m = 0; m < 4; ++m) { const size_t row = row0 + ai * 128 + m * 16;
;                         const f32x4 o = gv * (acc[ai][bj][m][n] + bv); u32x2 w; w.x = cvt_pk_bf16(o[0], o[1]); w.y = cvt_pk_bf16(o[2], o[3]);
;                         *(u32x2*)(O + row * 1024 + col) = w; } }
	v_pk_mul_f32 v[78:79], v[78:79], v[98:99]
	v_cvt_pk_bf16_f32 v76, v76, v77
	v_pk_mul_f32 v[74:75], v[74:75], v[98:99]
	v_cvt_pk_bf16_f32 v77, v78, v79
	global_store_dwordx2 v[108:109], v[76:77], off offset:32
	v_cvt_pk_bf16_f32 v72, v72, v73
	v_cvt_pk_bf16_f32 v73, v74, v75
	global_store_dwordx2 v[104:105], v[72:73], off offset:32
	v_pk_mul_f32 v[70:71], v[70:71], v[98:99]
	v_cvt_pk_bf16_f32 v68, v68, v69
	v_pk_mul_f32 v[66:67], v[66:67], v[98:99]
	v_cvt_pk_bf16_f32 v69, v70, v71
	global_store_dwordx2 v[100:101], v[68:69], off offset:32
	v_cvt_pk_bf16_f32 v64, v64, v65
	v_cvt_pk_bf16_f32 v65, v66, v67
	global_store_dwordx2 v[102:103], v[64:65], off offset:32
	s_nop 0
	v_mov_b32_e32 v64, v156
	v_mov_b32_e32 v65, v157
	v_mov_b32_e32 v66, v158
	v_mov_b32_e32 v67, v159
	v_pk_mul_f32 v[60:61], v[60:61], v[64:65]
	v_pk_mul_f32 v[56:57], v[56:57], v[64:65]
	v_pk_mul_f32 v[52:53], v[52:53], v[64:65]
	v_pk_mul_f32 v[48:49], v[48:49], v[64:65]
	v_pk_mul_f32 v[44:45], v[44:45], v[64:65]
	v_pk_mul_f32 v[40:41], v[40:41], v[64:65]
	v_pk_mul_f32 v[36:37], v[36:37], v[64:65]
	v_pk_mul_f32 v[32:33], v[32:33], v[64:65]
	v_pk_mul_f32 v[62:63], v[62:63], v[66:67]
	v_cvt_pk_bf16_f32 v60, v60, v61
	v_pk_mul_f32 v[58:59], v[58:59], v[66:67]
	v_cvt_pk_bf16_f32 v61, v62, v63
	global_store_dwordx2 v[124:125], v[60:61], off offset:256
	v_cvt_pk_bf16_f32 v56, v56, v57
	v_cvt_pk_bf16_f32 v57, v58, v59
	global_store_dwordx2 v[120:121], v[56:57], off offset:256
	v_pk_mul_f32 v[54:55], v[54:55], v[66:67]
	v_cvt_pk_bf16_f32 v52, v52, v53
	v_pk_mul_f32 v[50:51], v[50:51], v[66:67]
	v_cvt_pk_bf16_f32 v53, v54, v55
	global_store_dwordx2 v[116:117], v[52:53], off offset:256
	v_cvt_pk_bf16_f32 v48, v48, v49
	v_cvt_pk_bf16_f32 v49, v50, v51
	global_store_dwordx2 v[112:113], v[48:49], off offset:256
	v_pk_mul_f32 v[46:47], v[46:47], v[66:67]
	v_cvt_pk_bf16_f32 v44, v44, v45
	v_pk_mul_f32 v[42:43], v[42:43], v[66:67]
	v_cvt_pk_bf16_f32 v45, v46, v47
	global_store_dwordx2 v[108:109], v[44:45], off offset:256
	v_cvt_pk_bf16_f32 v40, v40, v41
	v_cvt_pk_bf16_f32 v41, v42, v43
	global_store_dwordx2 v[104:105], v[40:41], off offset:256
	v_pk_mul_f32 v[38:39], v[38:39], v[66:67]
	v_cvt_pk_bf16_f32 v36, v36, v37
	v_pk_mul_f32 v[34:35], v[34:35], v[66:67]
	v_cvt_pk_bf16_f32 v37, v38, v39
	global_store_dwordx2 v[100:101], v[36:37], off offset:256
	v_cvt_pk_bf16_f32 v32, v32, v33
	v_cvt_pk_bf16_f32 v33, v34, v35
	global_store_dwordx2 v[102:103], v[32:33], off offset:256
	s_nop 0
	v_mov_b32_e32 v32, v160
	v_mov_b32_e32 v33, v161
	v_mov_b32_e32 v34, v162
	v_mov_b32_e32 v35, v163
	v_pk_mul_f32 v[28:29], v[28:29], v[32:33]
	v_pk_mul_f32 v[24:25], v[24:25], v[32:33]
	v_pk_mul_f32 v[20:21], v[20:21], v[32:33]
	v_pk_mul_f32 v[16:17], v[16:17], v[32:33]
	v_pk_mul_f32 v[12:13], v[12:13], v[32:33]
	v_pk_mul_f32 v[8:9], v[8:9], v[32:33]
	v_pk_mul_f32 v[4:5], v[4:5], v[32:33]
	v_pk_mul_f32 v[0:1], v[0:1], v[32:33]
	v_pk_mul_f32 v[30:31], v[30:31], v[34:35]
	v_cvt_pk_bf16_f32 v28, v28, v29
	v_pk_mul_f32 v[26:27], v[26:27], v[34:35]
	v_cvt_pk_bf16_f32 v29, v30, v31
	global_store_dwordx2 v[124:125], v[28:29], off offset:288
	v_cvt_pk_bf16_f32 v24, v24, v25
	v_cvt_pk_bf16_f32 v25, v26, v27
	global_store_dwordx2 v[120:121], v[24:25], off offset:288
	v_pk_mul_f32 v[22:23], v[22:23], v[34:35]
	v_cvt_pk_bf16_f32 v20, v20, v21
	v_pk_mul_f32 v[18:19], v[18:19], v[34:35]
	v_cvt_pk_bf16_f32 v21, v22, v23
	global_store_dwordx2 v[116:117], v[20:21], off offset:288
	v_cvt_pk_bf16_f32 v16, v16, v17
	v_cvt_pk_bf16_f32 v17, v18, v19
	global_store_dwordx2 v[112:113], v[16:17], off offset:288
	v_pk_mul_f32 v[14:15], v[14:15], v[34:35]
	v_cvt_pk_bf16_f32 v12, v12, v13
	v_pk_mul_f32 v[10:11], v[10:11], v[34:35]
	v_cvt_pk_bf16_f32 v13, v14, v15
	global_store_dwordx2 v[108:109], v[12:13], off offset:288
	v_cvt_pk_bf16_f32 v8, v8, v9
	v_cvt_pk_bf16_f32 v9, v10, v11
	global_store_dwordx2 v[104:105], v[8:9], off offset:288
	v_pk_mul_f32 v[6:7], v[6:7], v[34:35]
	v_cvt_pk_bf16_f32 v4, v4, v5
	v_pk_mul_f32 v[2:3], v[2:3], v[34:35]
	v_cvt_pk_bf16_f32 v5, v6, v7
	global_store_dwordx2 v[100:101], v[4:5], off offset:288
	v_cvt_pk_bf16_f32 v0, v0, v1
	v_cvt_pk_bf16_f32 v1, v2, v3
	s_nop 1
	global_store_dwordx2 v[102:103], v[0:1], off offset:288
	s_cbranch_vccz .LBB0_318
	s_waitcnt vmcnt(0)
	s_cmpk_gt_u32 s22, 0xff
	s_cbranch_scc1 .LBB0_329
	s_barrier

; __device__ __forceinline__ f32x16 mfma32(bf16x8 a, bf16x8 b, f32x16 c) { return __builtin_amdgcn_mfma_f32_32x32x16_bf16(a, b, c, 0, 0, 0); }
;     ...
;                 const unsigned ioff = rowoff + (unsigned)ib * 8192u;
;                 f32x16 Ya;
; #pragma unroll
;                 for (int e = 0; e < 16; ++e) Ya[e] = 0.f;
; #pragma unroll
;                 for (int nb = 0; nb < 4; ++nb)
; #pragma unroll
;                     for (int sp = 0; sp < 2; ++sp) Ya = mfma32(pack_acc(H[nb], sp), t_ld44(TA, ioff, rx4, 4 * nb + 2 * sp, h), Ya);
;                 const float ci = cumL[32 * ib + r];
;                 const float mi = (ib == 0) ? mref[0] : (ib == 1) ? mref[1] : (ib == 2) ? mref[2] : mref[3];
.LBB0_432:
	v_lshl_add_u32 v87, s97, 13, v211
	v_add_u32_e32 v68, v87, v107
	v_xor_b32_e32 v173, 0x10, v107
	v_add_u32_e32 v70, v87, v173
	ds_read_b64 v[68:69], v68
	ds_read_b64 v[70:71], v70
	v_xor_b32_e32 v173, 0x20, v107
	v_add_u32_e32 v144, v87, v173
	v_xor_b32_e32 v173, 0x30, v107
	v_add_u32_e32 v146, v87, v173
	ds_read_b64 v[144:145], v144
	ds_read_b64 v[146:147], v146
	v_xor_b32_e32 v173, 0x40, v107
	v_add_u32_e32 v148, v87, v173
	v_xor_b32_e32 v173, 0x50, v107
	v_add_u32_e32 v150, v87, v173
	ds_read_b64 v[148:149], v148
	ds_read_b64 v[150:151], v150
	v_cvt_pk_bf16_f32 v64, v48, v49
	v_cvt_pk_bf16_f32 v65, v50, v51
	v_cvt_pk_bf16_f32 v66, v52, v53
	v_cvt_pk_bf16_f32 v67, v54, v55
	v_xor_b32_e32 v173, 0x60, v107
	v_add_u32_e32 v154, v87, v173
	v_xor_b32_e32 v173, 0x70, v107
	v_add_u32_e32 v156, v87, v173
	ds_read_b64 v[154:155], v154
	ds_read_b64 v[156:157], v156
	s_waitcnt lgkmcnt(6)
	v_mfma_f32_32x32x16_bf16 v[64:79], v[64:67], v[68:71], 0
	v_cvt_pk_bf16_f32 v80, v56, v57
	v_cvt_pk_bf16_f32 v81, v58, v59
	v_cvt_pk_bf16_f32 v82, v60, v61
	v_cvt_pk_bf16_f32 v83, v62, v63
	v_xor_b32_e32 v173, 0x80, v107
	v_add_u32_e32 v216, v87, v173
	v_xor_b32_e32 v173, 0x90, v107
	v_add_u32_e32 v218, v87, v173
	ds_read_b64 v[216:217], v216
	ds_read_b64 v[218:219], v218
	s_waitcnt lgkmcnt(6)
	v_mfma_f32_32x32x16_bf16 v[64:79], v[80:83], v[144:147], v[64:79]
	v_cvt_pk_bf16_f32 v80, v32, v33
	v_cvt_pk_bf16_f32 v81, v34, v35
	v_cvt_pk_bf16_f32 v82, v36, v37
	v_cvt_pk_bf16_f32 v83, v38, v39
	v_xor_b32_e32 v173, 0xa0, v107
	v_add_u32_e32 v144, v87, v173
	v_xor_b32_e32 v173, 0xb0, v107
	v_add_u32_e32 v146, v87, v173
	ds_read_b64 v[144:145], v144
	ds_read_b64 v[146:147], v146
	s_waitcnt lgkmcnt(6)
	v_mfma_f32_32x32x16_bf16 v[64:79], v[80:83], v[148:151], v[64:79]
	v_cvt_pk_bf16_f32 v80, v40, v41
	v_cvt_pk_bf16_f32 v81, v42, v43
	v_cvt_pk_bf16_f32 v82, v44, v45
	v_cvt_pk_bf16_f32 v83, v46, v47
	v_xor_b32_e32 v173, 0xc0, v107
	v_add_u32_e32 v148, v87, v173
	v_xor_b32_e32 v173, 0xd0, v107
	v_add_u32_e32 v150, v87, v173
	ds_read_b64 v[148:149], v148
	ds_read_b64 v[150:151], v150
	s_waitcnt lgkmcnt(6)
	v_mfma_f32_32x32x16_bf16 v[64:79], v[80:83], v[154:157], v[64:79]
	v_cvt_pk_bf16_f32 v80, v16, v17
	v_cvt_pk_bf16_f32 v81, v18, v19
	v_cvt_pk_bf16_f32 v82, v20, v21
	v_cvt_pk_bf16_f32 v83, v22, v23
	v_xor_b32_e32 v173, 0xe0, v107
	v_add_u32_e32 v154, v87, v173
	v_xor_b32_e32 v173, 0xf0, v107
	v_add_u32_e32 v156, v87, v173
	ds_read_b64 v[154:155], v154
	ds_read_b64 v[156:157], v156
	s_waitcnt lgkmcnt(6)
	v_mfma_f32_32x32x16_bf16 v[64:79], v[80:83], v[216:219], v[64:79]
	v_cvt_pk_bf16_f32 v80, v24, v25
	v_cvt_pk_bf16_f32 v81, v26, v27
	v_cvt_pk_bf16_f32 v82, v28, v29
	v_cvt_pk_bf16_f32 v83, v30, v31
	s_nop 1
	s_waitcnt lgkmcnt(4)
	v_mfma_f32_32x32x16_bf16 v[64:79], v[80:83], v[144:147], v[64:79]
	v_cvt_pk_bf16_f32 v80, v0, v1
	v_cvt_pk_bf16_f32 v81, v2, v3
	v_cvt_pk_bf16_f32 v82, v4, v5
	v_cvt_pk_bf16_f32 v83, v6, v7
	s_nop 1
	s_waitcnt lgkmcnt(2)
	v_mfma_f32_32x32x16_bf16 v[64:79], v[80:83], v[148:151], v[64:79]
	v_cvt_pk_bf16_f32 v80, v8, v9
	v_cvt_pk_bf16_f32 v81, v10, v11
	v_cvt_pk_bf16_f32 v82, v12, v13
	v_cvt_pk_bf16_f32 v83, v14, v15
	s_nop 1
	s_waitcnt lgkmcnt(0)
	v_mfma_f32_32x32x16_bf16 v[64:79], v[80:83], v[154:157], v[64:79]
	s_lshl_b32 s69, s97, 5
	v_or_b32_e32 v87, s69, v99
	v_lshl_add_u32 v80, v87, 2, s76
	ds_read_b32 v89, v80
	s_cmp_lt_i32 s97, 1
	v_mov_b32_e32 v80, s54
	s_cbranch_scc1 .LBB0_437
	s_cmp_lg_u32 s97, 1
	s_cbranch_scc0 .LBB0_435
	s_cmp_eq_u32 s97, 2
	v_mov_b32_e32 v80, s96
	s_cselect_b64 vcc, -1, 0
	v_cndmask_b32_e32 v80, 0, v80, vcc
	s_cbranch_execz .LBB0_436
	s_branch .LBB0_437

; #define LAS __attribute__((address_space(3)))
; __device__ __forceinline__ float bflo(unsigned w) { return __uint_as_float(w << 16); }
; __device__ __forceinline__ float bfhi(unsigned w) { return __uint_as_float(w & 0xffff0000u); }
;     ...
;                 for (int jb = (DIR ? ib + 1 : 0); jb < (DIR ? 4 : ib); ++jb) {
;                     f32x16 S;
;                     { const int bi2 = DIR ? 3 - ib : ib, bj2 = DIR ? 3 - jb : jb; const LAS u32x4* srcp = (const LAS u32x4*)(CBL + (bi2 * (bi2 + 1) / 2 + bj2) * 2048 + lane * 32);
;                       const u32x4 w0 = srcp[0], w1 = srcp[1];
;                       S[0] = bflo(w0.x); S[1] = bfhi(w0.x); S[2] = bflo(w0.y); S[3] = bfhi(w0.y); S[4] = bflo(w0.z); S[5] = bfhi(w0.z); S[6] = bflo(w0.w); S[7] = bfhi(w0.w);
;                       S[8] = bflo(w1.x); S[9] = bfhi(w1.x); S[10] = bflo(w1.y); S[11] = bfhi(w1.y); S[12] = bflo(w1.z); S[13] = bfhi(w1.z); S[14] = bflo(w1.w); S[15] = bfhi(w1.w); }
; #pragma unroll
;                     for (int q = 0; q < 4; ++q) { const f32x4 w4 = *(const LAS f32x4*)(wL + ib * 128 + 32 * jb + 8 * q + 4 * h);
; #pragma unroll
;                         for (int k = 0; k < 4; ++k) S[4 * q + k] *= w4[k]; }
.LBB0_439:
	v_add_u32_e32 v83, 0x21800, v81
	v_add_u32_e32 v91, 0x18680, v82
	ds_read_b128 v[144:147], v83
	ds_read_b128 v[216:219], v91
	ds_read_b128 v[220:223], v91 offset:32
	ds_read_b128 v[148:151], v83 offset:16
	ds_read_b128 v[224:227], v91 offset:64
	ds_read_b128 v[152:155], v91 offset:96
	s_add_i32 s62, s62, -1
	s_add_i32 s66, s66, 32
	v_add_u32_e32 v81, 0xfffff800, v81
	v_add_u32_e32 v82, 0x80, v82
	s_waitcnt lgkmcnt(3)
	v_lshlrev_b32_e32 v83, 16, v144
	v_and_b32_e32 v91, 0xffff0000, v144
	v_mul_f32_e32 v216, v216, v83
	v_mul_f32_e32 v217, v217, v91
	v_lshlrev_b32_e32 v83, 16, v145
	v_and_b32_e32 v91, 0xffff0000, v145
	v_mul_f32_e32 v218, v218, v83
	v_mul_f32_e32 v219, v219, v91
	v_lshlrev_b32_e32 v83, 16, v146
	v_and_b32_e32 v91, 0xffff0000, v146
	v_mul_f32_e32 v220, v220, v83
	v_mul_f32_e32 v221, v221, v91
	v_lshlrev_b32_e32 v83, 16, v147
	v_and_b32_e32 v91, 0xffff0000, v147
	v_mul_f32_e32 v222, v222, v83
	v_mul_f32_e32 v223, v223, v91
	v_cvt_pk_bf16_f32 v194, v216, v217
	v_cvt_pk_bf16_f32 v195, v218, v219
	v_cvt_pk_bf16_f32 v196, v220, v221
	v_cvt_pk_bf16_f32 v197, v222, v223
	s_cmp_eq_u32 s66, 64
	s_cbranch_scc1 .Lssd_a_jb_1
	s_cmp_eq_u32 s66, 96
	s_cbranch_scc1 .Lssd_a_jb_2
	v_mov_b32_e32 v144, v228
	v_mov_b32_e32 v145, v229
	v_mov_b32_e32 v146, v230
	v_mov_b32_e32 v147, v231
	v_mov_b32_e32 v248, v232
	v_mov_b32_e32 v249, v233
	v_mov_b32_e32 v250, v234
	v_mov_b32_e32 v251, v235
	s_branch .Lssd_a_jb_done

; #define LAS __attribute__((address_space(3)))
; __device__ __forceinline__ f32x16 mfma32(bf16x8 a, bf16x8 b, f32x16 c) { return __builtin_amdgcn_mfma_f32_32x32x16_bf16(a, b, c, 0, 0, 0); }
;     ...
;                     Ya = mfma32(ld44(XT + 32 * jb + 4 * h), pack_acc(S, 0), Ya); Ya = mfma32(ld44(XT + 32 * jb + 16 + 4 * h), pack_acc(S, 1), Ya);
;                 }
;     ...
;                     { const int bi2 = DIR ? 3 - ib : ib, bj2 = DIR ? 3 - jb : jb; const LAS u32x4* srcp = (const LAS u32x4*)(CBL + (bi2 * (bi2 + 1) / 2 + bj2) * 2048 + lane * 32);
.Lssd_a_jb_done:
	s_cmp_eq_u32 s62, 0
	v_mfma_f32_32x32x16_bf16 v[64:79], v[144:147], v[194:197], v[64:79]
	s_waitcnt lgkmcnt(0)
	v_lshlrev_b32_e32 v83, 16, v148
	v_and_b32_e32 v91, 0xffff0000, v148
	v_mul_f32_e32 v224, v224, v83
	v_mul_f32_e32 v225, v225, v91
	v_lshlrev_b32_e32 v83, 16, v149
	v_and_b32_e32 v91, 0xffff0000, v149
	v_mul_f32_e32 v226, v226, v83
	v_mul_f32_e32 v227, v227, v91
	v_lshlrev_b32_e32 v83, 16, v150
	v_and_b32_e32 v91, 0xffff0000, v150
	v_mul_f32_e32 v152, v152, v83
	v_mul_f32_e32 v153, v153, v91
	v_lshlrev_b32_e32 v83, 16, v151
	v_and_b32_e32 v91, 0xffff0000, v151
	v_mul_f32_e32 v154, v154, v83
	v_mul_f32_e32 v155, v155, v91
	v_cvt_pk_bf16_f32 v148, v224, v225
	v_cvt_pk_bf16_f32 v149, v226, v227
	v_cvt_pk_bf16_f32 v150, v152, v153
	v_cvt_pk_bf16_f32 v151, v154, v155
	s_nop 1
	v_mfma_f32_32x32x16_bf16 v[64:79], v[248:251], v[148:151], v[64:79]
	s_cbranch_scc0 .LBB0_439
	s_sub_i32 s62, 3, s97
	s_sub_i32 s63, 4, s97
	s_mul_i32 s63, s62, s63
	s_lshr_b32 s63, s63, 1
	s_add_i32 s63, s63, s62
	s_lshl_b32 s62, s63, 11
	s_branch .LBB0_431

; __device__ __forceinline__ f32x16 mfma32(bf16x8 a, bf16x8 b, f32x16 c) { return __builtin_amdgcn_mfma_f32_32x32x16_bf16(a, b, c, 0, 0, 0); }
;     ...
;                 const unsigned ioff = rowoff + (unsigned)ib * 8192u;
;                 f32x16 Ya;
; #pragma unroll
;                 for (int e = 0; e < 16; ++e) Ya[e] = 0.f;
; #pragma unroll
;                 for (int nb = 0; nb < 4; ++nb)
; #pragma unroll
;                     for (int sp = 0; sp < 2; ++sp) Ya = mfma32(pack_acc(H[nb], sp), t_ld44(TA, ioff, rx4, 4 * nb + 2 * sp, h), Ya);
;                 const float ci = cumL[32 * ib + r];
;                 const float mi = (ib == 0) ? mref[0] : (ib == 1) ? mref[1] : (ib == 2) ? mref[2] : mref[3];
.LBB0_454:
	v_lshl_add_u32 v88, s66, 13, v211
	v_add_u32_e32 v68, v88, v107
	v_xor_b32_e32 v173, 0x10, v107
	v_add_u32_e32 v70, v88, v173
	ds_read_b64 v[68:69], v68
	ds_read_b64 v[70:71], v70
	v_xor_b32_e32 v173, 0x20, v107
	v_add_u32_e32 v84, v88, v173
	v_xor_b32_e32 v173, 0x30, v107
	v_add_u32_e32 v86, v88, v173
	ds_read_b64 v[84:85], v84
	ds_read_b64 v[86:87], v86
	v_xor_b32_e32 v173, 0x40, v107
	v_add_u32_e32 v220, v88, v173
	v_xor_b32_e32 v173, 0x50, v107
	v_add_u32_e32 v222, v88, v173
	ds_read_b64 v[220:221], v220
	ds_read_b64 v[222:223], v222
	v_cvt_pk_bf16_f32 v64, v48, v49
	v_cvt_pk_bf16_f32 v65, v50, v51
	v_cvt_pk_bf16_f32 v66, v52, v53
	v_cvt_pk_bf16_f32 v67, v54, v55
	v_xor_b32_e32 v173, 0x60, v107
	v_add_u32_e32 v224, v88, v173
	v_xor_b32_e32 v173, 0x70, v107
	v_add_u32_e32 v226, v88, v173
	ds_read_b64 v[224:225], v224
	ds_read_b64 v[226:227], v226
	s_waitcnt lgkmcnt(6)
	v_mfma_f32_32x32x16_bf16 v[64:79], v[64:67], v[68:71], 0
	v_cvt_pk_bf16_f32 v80, v56, v57
	v_cvt_pk_bf16_f32 v81, v58, v59
	v_cvt_pk_bf16_f32 v82, v60, v61
	v_cvt_pk_bf16_f32 v83, v62, v63
	v_xor_b32_e32 v173, 0x80, v107
	v_add_u32_e32 v128, v88, v173
	v_xor_b32_e32 v173, 0x90, v107
	v_add_u32_e32 v130, v88, v173
	ds_read_b64 v[128:129], v128
	ds_read_b64 v[130:131], v130
	s_waitcnt lgkmcnt(6)
	v_mfma_f32_32x32x16_bf16 v[64:79], v[80:83], v[84:87], v[64:79]
	v_cvt_pk_bf16_f32 v80, v32, v33
	v_cvt_pk_bf16_f32 v81, v34, v35
	v_cvt_pk_bf16_f32 v82, v36, v37
	v_cvt_pk_bf16_f32 v83, v38, v39
	v_xor_b32_e32 v173, 0xa0, v107
	v_add_u32_e32 v84, v88, v173
	v_xor_b32_e32 v173, 0xb0, v107
	v_add_u32_e32 v86, v88, v173
	ds_read_b64 v[84:85], v84
	ds_read_b64 v[86:87], v86
	s_waitcnt lgkmcnt(6)
	v_mfma_f32_32x32x16_bf16 v[64:79], v[80:83], v[220:223], v[64:79]
	v_cvt_pk_bf16_f32 v80, v40, v41
	v_cvt_pk_bf16_f32 v81, v42, v43
	v_cvt_pk_bf16_f32 v82, v44, v45
	v_cvt_pk_bf16_f32 v83, v46, v47
	v_xor_b32_e32 v173, 0xc0, v107
	v_add_u32_e32 v220, v88, v173
	v_xor_b32_e32 v173, 0xd0, v107
	v_add_u32_e32 v222, v88, v173
	ds_read_b64 v[220:221], v220
	ds_read_b64 v[222:223], v222
	s_waitcnt lgkmcnt(6)
	v_mfma_f32_32x32x16_bf16 v[64:79], v[80:83], v[224:227], v[64:79]
	v_cvt_pk_bf16_f32 v80, v16, v17
	v_cvt_pk_bf16_f32 v81, v18, v19
	v_cvt_pk_bf16_f32 v82, v20, v21
	v_cvt_pk_bf16_f32 v83, v22, v23
	v_xor_b32_e32 v173, 0xe0, v107
	v_add_u32_e32 v224, v88, v173
	v_xor_b32_e32 v173, 0xf0, v107
	v_add_u32_e32 v226, v88, v173
	ds_read_b64 v[224:225], v224
	ds_read_b64 v[226:227], v226
	s_waitcnt lgkmcnt(6)
	v_mfma_f32_32x32x16_bf16 v[64:79], v[80:83], v[128:131], v[64:79]
	v_cvt_pk_bf16_f32 v80, v24, v25
	v_cvt_pk_bf16_f32 v81, v26, v27
	v_cvt_pk_bf16_f32 v82, v28, v29
	v_cvt_pk_bf16_f32 v83, v30, v31
	s_nop 1
	s_waitcnt lgkmcnt(4)
	v_mfma_f32_32x32x16_bf16 v[64:79], v[80:83], v[84:87], v[64:79]
	v_cvt_pk_bf16_f32 v80, v0, v1
	v_cvt_pk_bf16_f32 v81, v2, v3
	v_cvt_pk_bf16_f32 v82, v4, v5
	v_cvt_pk_bf16_f32 v83, v6, v7
	s_nop 1
	s_waitcnt lgkmcnt(2)
	v_mfma_f32_32x32x16_bf16 v[64:79], v[80:83], v[220:223], v[64:79]
	v_cvt_pk_bf16_f32 v80, v8, v9
	v_cvt_pk_bf16_f32 v81, v10, v11
	v_cvt_pk_bf16_f32 v82, v12, v13
	v_cvt_pk_bf16_f32 v83, v14, v15
	s_nop 1
	s_waitcnt lgkmcnt(0)
	v_mfma_f32_32x32x16_bf16 v[64:79], v[80:83], v[224:227], v[64:79]
	s_lshl_b32 s59, s66, 5
	v_or_b32_e32 v137, s59, v99
	v_lshl_add_u32 v80, v137, 2, s76
	ds_read_b32 v139, v80
	s_cmp_lt_i32 s66, 1
	s_cbranch_scc1 .LBB0_458
	s_cmp_eq_u32 s66, 1
	s_mov_b64 s[62:63], -1
	s_cbranch_scc0 .LBB0_457
	s_mov_b64 s[62:63], 0

; #define LAS __attribute__((address_space(3)))
; __device__ __forceinline__ float bflo(unsigned w) { return __uint_as_float(w << 16); }
; __device__ __forceinline__ float bfhi(unsigned w) { return __uint_as_float(w & 0xffff0000u); }
;     ...
;                 for (int jb = (DIR ? ib + 1 : 0); jb < (DIR ? 4 : ib); ++jb) {
;                     f32x16 S;
;                     { const int bi2 = DIR ? 3 - ib : ib, bj2 = DIR ? 3 - jb : jb; const LAS u32x4* srcp = (const LAS u32x4*)(CBL + (bi2 * (bi2 + 1) / 2 + bj2) * 2048 + lane * 32);
;                       const u32x4 w0 = srcp[0], w1 = srcp[1];
;                       S[0] = bflo(w0.x); S[1] = bfhi(w0.x); S[2] = bflo(w0.y); S[3] = bfhi(w0.y); S[4] = bflo(w0.z); S[5] = bfhi(w0.z); S[6] = bflo(w0.w); S[7] = bfhi(w0.w);
;                       S[8] = bflo(w1.x); S[9] = bfhi(w1.x); S[10] = bflo(w1.y); S[11] = bfhi(w1.y); S[12] = bflo(w1.z); S[13] = bfhi(w1.z); S[14] = bflo(w1.w); S[15] = bfhi(w1.w); }
; #pragma unroll
;                     for (int q = 0; q < 4; ++q) { const f32x4 w4 = *(const LAS f32x4*)(wL + ib * 128 + 32 * jb + 8 * q + 4 * h);
; #pragma unroll
;                         for (int k = 0; k < 4; ++k) S[4 * q + k] *= w4[k]; }
.LBB0_464:
	v_add_u32_e32 v232, 0x20000, v192
	v_add_u32_e32 v233, 0x18600, v219
	ds_read_b128 v[220:223], v232
	ds_read_b128 v[228:231], v233
	ds_read_b128 v[246:249], v233 offset:32
	ds_read_b128 v[224:227], v232 offset:16
	ds_read_b128 v[194:197], v233 offset:64
	ds_read_b128 v[88:91], v233 offset:96
	s_add_i32 s62, s62, -1
	v_add_u32_e32 v192, 0x800, v192
	v_add_u32_e32 v219, 0x80, v219
	s_waitcnt lgkmcnt(3)
	v_lshlrev_b32_e32 v250, 16, v220
	v_and_b32_e32 v251, 0xffff0000, v220
	v_mul_f32_e32 v228, v228, v250
	v_mul_f32_e32 v229, v229, v251
	v_lshlrev_b32_e32 v250, 16, v221
	v_and_b32_e32 v251, 0xffff0000, v221
	v_mul_f32_e32 v230, v230, v250
	v_mul_f32_e32 v231, v231, v251
	v_lshlrev_b32_e32 v250, 16, v222
	v_and_b32_e32 v251, 0xffff0000, v222
	v_mul_f32_e32 v246, v246, v250
	v_mul_f32_e32 v247, v247, v251
	v_lshlrev_b32_e32 v250, 16, v223
	v_and_b32_e32 v251, 0xffff0000, v223
	v_mul_f32_e32 v248, v248, v250
	v_mul_f32_e32 v249, v249, v251
	v_cvt_pk_bf16_f32 v84, v228, v229
	v_cvt_pk_bf16_f32 v85, v230, v231
	v_cvt_pk_bf16_f32 v86, v246, v247
	v_cvt_pk_bf16_f32 v87, v248, v249
	s_sub_i32 s100, s66, s62
	s_cmp_eq_u32 s100, 1
	s_cbranch_scc1 .Lssd_b_jb_0
	s_cmp_eq_u32 s100, 2
	s_cbranch_scc1 .Lssd_b_jb_1
	v_mov_b32_e32 v220, v204
	v_mov_b32_e32 v221, v205
	v_mov_b32_e32 v222, v206
	v_mov_b32_e32 v223, v207
	v_mov_b32_e32 v128, v234
	v_mov_b32_e32 v129, v235
	v_mov_b32_e32 v130, v244
	v_mov_b32_e32 v131, v245
	s_branch .Lssd_b_jb_done

; __device__ __forceinline__ f32x16 mfma32(bf16x8 a, bf16x8 b, f32x16 c) { return __builtin_amdgcn_mfma_f32_32x32x16_bf16(a, b, c, 0, 0, 0); }
;     ...
;                     Ya = mfma32(ld44(XT + 32 * jb + 4 * h), pack_acc(S, 0), Ya); Ya = mfma32(ld44(XT + 32 * jb + 16 + 4 * h), pack_acc(S, 1), Ya);
;                 }
.Lssd_b_jb_done:
	s_cmp_eq_u32 s62, 0
	v_mfma_f32_32x32x16_bf16 v[64:79], v[220:223], v[84:87], v[64:79]
	s_waitcnt lgkmcnt(0)
	v_lshlrev_b32_e32 v250, 16, v224
	v_and_b32_e32 v251, 0xffff0000, v224
	v_mul_f32_e32 v194, v194, v250
	v_mul_f32_e32 v195, v195, v251
	v_lshlrev_b32_e32 v250, 16, v225
	v_and_b32_e32 v251, 0xffff0000, v225
	v_mul_f32_e32 v196, v196, v250
	v_mul_f32_e32 v197, v197, v251
	v_lshlrev_b32_e32 v250, 16, v226
	v_and_b32_e32 v251, 0xffff0000, v226
	v_mul_f32_e32 v88, v88, v250
	v_mul_f32_e32 v89, v89, v251
	v_lshlrev_b32_e32 v250, 16, v227
	v_and_b32_e32 v251, 0xffff0000, v227
	v_mul_f32_e32 v90, v90, v250
	v_mul_f32_e32 v91, v91, v251
	v_cvt_pk_bf16_f32 v224, v194, v195
	v_cvt_pk_bf16_f32 v225, v196, v197
	v_cvt_pk_bf16_f32 v226, v88, v89
	v_cvt_pk_bf16_f32 v227, v90, v91
	s_nop 1
	v_mfma_f32_32x32x16_bf16 v[64:79], v[128:131], v[224:227], v[64:79]
	s_cbranch_scc0 .LBB0_464
	s_mov_b32 s62, s33
	s_branch .LBB0_453
